# trailing half's inter-unit barrier moved to the K-loop entry (P1, P6): its next-unit setup no longer sits inside the leading half's first MFMA block
# baseline (speedup 1.0000x reference)
; #define PG8_BAR __builtin_amdgcn_s_barrier()
; template <class Epi, class Sched, bool ALIGN_EPI = false, bool SP2 = false>
; __device__ __forceinline__ void gemm_phase(PG8_LAS unsigned char* lds, const Gemm g, const Sched& S, const Epi& E) {
;     int tid_ = threadIdx.x; asm volatile("" : "+v"(tid_));
;     const int tid = tid_, wid = __builtin_amdgcn_readfirstlane(tid >> 6), lane = tid & 63, wr = wid >> 2, wc = wid & 3, fr = lane & 15, fq = lane >> 4;
;     int K_ = g.K; asm volatile("" : "+s"(K_));
;     const int K = K_, nt = K / BK;
;     unsigned voffA[2], voffB[2];
; #pragma unroll
;     for (int i = 0; i < 2; ++i) { int R, C; stage_rc(tid * 16 + i * 8192, R, C); const int Rb = Epi::PERM ? ((R & ~31) + perm32(R & 31)) : R;
;         voffA[i] = (unsigned)(R * K + C) * 2u; voffB[i] = (unsigned)(Rb * K + C) * 2u; }
;     const size_t kstep = (size_t)(BK * 2);
;     const size_t hstep = (size_t)HALF * K * 2;
;     const size_t tstep = 2 * hstep;
;     const unsigned ldsw = (unsigned)wid * 1024u;
;     const int aoff = lds_byte(wr * 64 + fr, fq * 8), boff = lds_byte(wc * 32 + fr, fq * 8);
;     ...
;     Unit cur, nxt; int ui = 0;
;     if (!S.next(0, cur)) return;
;     f32x4 acc[2][2][4][2];
; #pragma unroll
;     for (int a = 0; a < 2; ++a)
; #pragma unroll
;         for (int b = 0; b < 2; ++b)
; #pragma unroll
;             for (int m = 0; m < 4; ++m)
; #pragma unroll
;                 for (int n = 0; n < 2; ++n) acc[a][b][m][n] = (f32x4){0.f, 0.f, 0.f, 0.f};
;     bf16x8 At[4][2], B0[2][2], B1[2][2];
;     const char* cA = (const char*)g.A + (size_t)cur.pm * tstep; const char* cB = (const char*)g.Bt + (size_t)cur.pn * tstep;
;     S.a_ready(cur);
;     if constexpr (SP2) {
;         PG8_STAGE(PG8_SB(0, 0), cB, voffB); PG8_STAGE(PG8_SB(0, 1), cB + hstep, voffB); PG8_STAGE(PG8_SA(0, 0), cA, voffA); PG8_STAGE(PG8_SA(0, 1), cA + hstep, voffA);
;         if (wr == 1) PG8_BAR;
;         PG8_WAIT_V(2); PG8_BAR;
;         PG8_STAGE(PG8_SB(1, 0), cB + kstep, voffB); PG8_STAGE(PG8_SA(1, 0), cA + kstep, voffA); PG8_STAGE(PG8_SB(1, 1), cB + hstep + kstep, voffB);
;         PG8_WAIT_V(6); PG8_BAR;
;     } else {
;         PG8_STAGE(PG8_SB(0, 0), cB, voffB); PG8_STAGE(PG8_SA(0, 0), cA, voffA); PG8_STAGE(PG8_SB(0, 1), cB + hstep, voffB); PG8_STAGE(PG8_SA(0, 1), cA + hstep, voffA);
;         if (wr == 1) PG8_BAR;
;         PG8_WAIT_V(4); PG8_BAR;
.LBB0_249:
	s_cmp_lt_i32 s28, 2
	s_cselect_b64 s[4:5], -1, 0
	s_add_u32 s52, s26, 0x2900000
	s_addc_u32 s53, s27, 0
	s_add_u32 s46, s26, 0x8680000
	s_addc_u32 s47, s27, 0
	s_cmpk_eq_i32 s30, 0x100
	s_cselect_b64 s[54:55], -1, 0
	s_cmpk_lg_i32 s30, 0x100
	s_cselect_b64 s[50:51], -1, 0
	s_and_b64 s[10:11], s[4:5], s[6:7]
	s_andn2_b64 vcc, exec, s[10:11]
	s_cbranch_vccnz .LBB0_291
	s_mov_b32 s86, -1
	s_mov_b32 s87, 0
	v_lshlrev_b32_e32 v236, 4, v192
	v_mov_b32_e32 v237, 0
	v_lshl_add_u64 v[236:237], s[44:45], 0, v[236:237]
	v_mov_b32_e32 v12, v192
	s_movk_i32 s6, 0x400
	v_readfirstlane_b32 s9, v12
	s_cmpk_gt_i32 s2, 0x5d7
	s_cbranch_scc1 .LBB0_271
	v_lshlrev_b32_e32 v0, 4, v12
	v_add_u32_e32 v1, 0x2000, v0
	v_ashrrev_i32_e32 v2, 31, v1
	v_lshrrev_b32_e32 v2, 22, v2
	v_add_u32_e32 v2, v1, v2
	v_ashrrev_i32_e32 v2, 10, v2
	v_mul_i32_i24_e32 v3, 0x400, v2
	v_sub_u32_e32 v1, v1, v3
	v_lshrrev_b32_e32 v3, 4, v1
	v_bitop3_b32 v1, v3, v1, 32 bitop3:0x6c
	v_ashrrev_i32_e32 v3, 31, v1
	v_lshrrev_b32_e32 v3, 26, v3
	v_add_u32_e32 v3, v1, v3
	v_lshlrev_b32_e32 v5, 3, v2
	v_ashrrev_i32_e32 v4, 6, v3
	v_and_b32_e32 v5, -16, v5
	v_lshlrev_b32_e32 v2, 5, v2
	v_add_u32_e32 v5, v4, v5
	v_and_b32_e32 v13, 32, v2
	v_and_b32_e32 v2, 0xc0, v3
	v_and_b32_e32 v4, 3, v4
	s_mov_b32 s4, 0x7fffffe0
	v_lshrrev_b32_e32 v6, 2, v5
	v_lshlrev_b32_e32 v7, 1, v5
	v_sub_u32_e32 v1, v1, v2
	v_mov_b32_e32 v2, 1
	v_and_or_b32 v4, v5, s4, v4
	v_and_b32_e32 v6, 4, v6
	v_and_b32_e32 v7, 24, v7
	v_ashrrev_i16_sdwa v1, v2, sext(v1) dst_sel:DWORD dst_unused:UNUSED_PAD src0_sel:DWORD src1_sel:BYTE_0
	v_or3_b32 v4, v4, v6, v7
	v_bfe_i32 v14, v1, 0, 16
	v_mul_lo_u32 v4, v4, s6
	v_add_u32_e32 v1, v13, v14
	v_mul_lo_u32 v15, v5, s6
	v_add_lshl_u32 v130, v4, v1, 1
	v_add_lshl_u32 v132, v1, v15, 1
	v_bfe_i32 v1, v12, 27, 1
	v_lshrrev_b32_e32 v1, 22, v1
	v_add_u32_e32 v1, v0, v1
	v_and_b32_e32 v1, 0xfffffc00, v1
	v_sub_u32_e32 v0, v0, v1
	v_lshrrev_b32_e32 v1, 4, v0
	v_ashrrev_i32_e32 v4, 31, v12
	v_bitop3_b32 v0, v1, v0, 32 bitop3:0x6c
	v_lshrrev_b32_e32 v4, 26, v4
	v_ashrrev_i32_e32 v1, 31, v0
	v_add_u32_e32 v4, v12, v4
	v_lshrrev_b32_e32 v1, 26, v1
	v_ashrrev_i32_e32 v4, 6, v4
	v_add_u32_e32 v1, v0, v1
	v_lshlrev_b32_e32 v5, 3, v4
	v_ashrrev_i32_e32 v3, 6, v1
	v_and_b32_e32 v5, -16, v5
	v_add_u32_e32 v5, v3, v5
	v_and_b32_e32 v3, 3, v3
	s_ashr_i32 s39, s2, 31
	v_and_or_b32 v3, v5, s4, v3
	s_lshr_b32 s4, s39, 29
	s_add_i32 s4, s2, s4
	s_ashr_i32 s20, s9, 6
	s_ashr_i32 s7, s6, 31
	s_ashr_i32 s5, s4, 3
	s_and_b32 s4, s4, -8
	s_ashr_i32 s21, s9, 8
	s_lshl_b64 s[12:13], s[6:7], 8
	s_lshl_b64 s[14:15], s[6:7], 9
	s_lshl_b32 s3, s20, 10
	s_sub_i32 s4, s2, s4
	s_cmp_lt_i32 s4, 0
	s_movk_i32 s49, 0xbc
	s_cselect_b32 s8, s49, 0xbb
	s_mul_i32 s4, s4, s8
	s_add_i32 s4, s4, s5
	s_mul_hi_i32 s5, s4, 0x2e8ba2e9
	s_lshr_b32 s8, s5, 31
	s_ashr_i32 s5, s5, 5
	v_and_b32_e32 v1, 0xc0, v1
	s_add_i32 s5, s5, s8
	v_lshrrev_b32_e32 v6, 2, v5
	v_lshlrev_b32_e32 v7, 1, v5
	v_sub_u32_e32 v0, v0, v1
	s_lshl_b32 s16, s5, 3
	v_and_b32_e32 v6, 4, v6
	v_and_b32_e32 v7, 24, v7
	v_lshlrev_b32_e32 v4, 5, v4
	v_ashrrev_i16_sdwa v0, v2, sext(v0) dst_sel:DWORD dst_unused:UNUSED_PAD src0_sel:DWORD src1_sel:BYTE_0
	s_sub_i32 s8, 0x44, s16
	s_mulk_i32 s5, 0xb0
	v_or3_b32 v3, v3, v6, v7
	v_and_b32_e32 v16, 32, v4
	v_bfe_i32 v17, v0, 0, 16
	s_min_u32 s17, s8, 8
	s_sub_i32 s18, s4, s5
	v_mul_lo_u32 v3, v3, s6
	v_add_u32_e32 v0, v16, v17
	s_sext_i32_i16 s4, s18
	v_cvt_f32_ubyte0_e32 v2, s17
	v_add_lshl_u32 v134, v3, v0, 1
	v_cvt_f32_i32_e32 v1, s4
	v_rcp_iflag_f32_e32 v3, v2
	v_mul_lo_u32 v18, v5, s6
	v_add_lshl_u32 v136, v0, v18, 1
	s_ashr_i32 s4, s4, 30
	v_mul_f32_e32 v0, v1, v3
	v_trunc_f32_e32 v0, v0
	v_fma_f32 v1, -v0, v2, v1
	v_cvt_i32_f32_e32 v0, v0
	s_or_b32 s8, s4, 1
	v_cmp_ge_f32_e64 s[4:5], |v1|, v2
	s_and_b64 s[4:5], s[4:5], exec
	s_cselect_b32 s4, s8, 0
	v_readfirstlane_b32 s5, v0
	s_add_i32 s8, s5, s4
	s_mul_i32 s4, s8, s17
	s_sub_i32 s4, s18, s4
	s_sext_i32_i16 s4, s4
	s_add_i32 s4, s16, s4
	s_ashr_i32 s5, s4, 31
	s_mul_i32 s5, s14, s5
	s_mul_hi_u32 s16, s14, s4
	s_add_i32 s5, s16, s5
	s_lshr_b64 s[16:17], s[6:7], 23
	s_mul_i32 s17, s16, s4
	s_bfe_i64 s[18:19], s[8:9], 0x100000
	s_add_i32 s5, s5, s17
	s_mul_i32 s17, s14, s19
	s_mul_hi_u32 s19, s14, s18
	s_add_i32 s17, s19, s17
	s_mul_i32 s16, s16, s18
	s_add_i32 s17, s17, s16
	s_mul_i32 s16, s14, s18
	s_add_u32 s42, s26, s16
	s_addc_u32 s43, s27, s17
	s_add_i32 s56, s3, 0
	s_add_i32 m0, s56, 0x10000
	s_mul_i32 s22, s14, s4
	global_load_lds_dwordx4 v134, s[42:43]
	s_add_i32 m0, s56, 0x12000
	s_add_u32 s16, s42, s12
	global_load_lds_dwordx4 v130, s[42:43]
	s_addc_u32 s17, s43, s13
	s_add_i32 m0, s56, 0x14000
	v_mov_b32_e32 v135, 0
	global_load_lds_dwordx4 v134, s[16:17]
	s_add_i32 m0, s56, 0x16000
	s_add_u32 s40, s34, s22
	s_addc_u32 s41, s35, s5
	s_add_i32 s57, s56, 0x2000
	global_load_lds_dwordx4 v130, s[16:17]
	s_mov_b32 m0, s56
	s_add_u32 s18, s40, s12
	global_load_lds_dwordx4 v136, s[40:41]
	s_mov_b32 m0, s57
	s_addc_u32 s19, s41, s13
	s_add_i32 s58, s56, 0x4000
	global_load_lds_dwordx4 v132, s[40:41]
	s_mov_b32 m0, s58
	s_add_i32 s59, s56, 0x6000
	global_load_lds_dwordx4 v136, s[18:19]
	s_mov_b32 m0, s59
	v_mov_b32_e32 v131, v135
	global_load_lds_dwordx4 v132, s[18:19]
	v_mov_b32_e32 v137, v135
	v_mov_b32_e32 v133, v135
	s_cmp_eq_u32 s21, 1
	s_mov_b32 s60, 0
	v_lshl_add_u64 v[8:9], s[42:43], 0, v[134:135]
	v_lshl_add_u64 v[4:5], s[42:43], 0, v[130:131]
	v_lshl_add_u64 v[2:3], s[16:17], 0, v[134:135]
	v_lshl_add_u64 v[0:1], s[16:17], 0, v[130:131]
	v_lshl_add_u64 v[6:7], s[40:41], 0, v[136:137]
	s_cselect_b64 s[16:17], -1, 0
	s_cmp_lg_u32 s21, 1
	v_lshl_add_u64 v[10:11], s[40:41], 0, v[132:133]
	s_cbranch_scc1 .LBB0_253
	s_barrier

; template <class Epi, class Sched, bool ALIGN_EPI = false, bool SP2 = false>
; __device__ __forceinline__ void gemm_phase(PG8_LAS unsigned char* lds, const Gemm g, const Sched& S, const Epi& E) {
;     ...
;         for (int t = 0; t < nt; t += 2) {
;             const bool last = (t == nt - 2);
;             const char* a1 = cA + (size_t)(t + 1) * kstep;
;             const char* a2 = last ? nA : cA + (size_t)(t + 2) * kstep; const char* b2 = last ? nB : cB + (size_t)(t + 2) * kstep;
;             const char* a3 = a2 + kstep; const char* b3 = b2 + kstep;
;     ...
; #pragma unroll
;         for (int a = 0; a < 2; ++a)
; #pragma unroll
;             for (int b = 0; b < 2; ++b)
; #pragma unroll
;                 for (int m = 0; m < 4; ++m)
; #pragma unroll
;                     for (int n = 0; n < 2; ++n) acc[a][b][m][n] = (f32x4){0.f, 0.f, 0.f, 0.f};
;         cur = nxt; cA = nA; cB = nB; ++ui;
.LBB0_262:
	v_mov_b64_e32 v[0:1], 0
	v_mov_b64_e32 v[2:3], 0
	v_mov_b64_e32 v[4:5], 0
	v_mov_b64_e32 v[6:7], 0
	v_mov_b64_e32 v[8:9], 0
	v_mov_b64_e32 v[10:11], 0
	v_mov_b64_e32 v[12:13], 0
	v_mov_b64_e32 v[14:15], 0
	v_mov_b64_e32 v[16:17], 0
	v_mov_b64_e32 v[18:19], 0
	v_mov_b64_e32 v[20:21], 0
	v_mov_b64_e32 v[22:23], 0
	v_mov_b64_e32 v[24:25], 0
	v_mov_b64_e32 v[26:27], 0
	v_mov_b64_e32 v[28:29], 0
	v_mov_b64_e32 v[30:31], 0
	v_mov_b64_e32 v[32:33], 0
	v_mov_b64_e32 v[34:35], 0
	v_mov_b64_e32 v[36:37], 0
	v_mov_b64_e32 v[38:39], 0
	v_mov_b64_e32 v[40:41], 0
	v_mov_b64_e32 v[42:43], 0
	v_mov_b64_e32 v[44:45], 0
	v_mov_b64_e32 v[46:47], 0
	v_mov_b64_e32 v[48:49], 0
	v_mov_b64_e32 v[50:51], 0
	v_mov_b64_e32 v[52:53], 0
	v_mov_b64_e32 v[54:55], 0
	v_mov_b64_e32 v[56:57], 0
	v_mov_b64_e32 v[58:59], 0
	v_mov_b64_e32 v[60:61], 0
	v_mov_b64_e32 v[62:63], 0
	v_mov_b64_e32 v[64:65], 0
	v_mov_b64_e32 v[66:67], 0
	v_mov_b64_e32 v[68:69], 0
	v_mov_b64_e32 v[70:71], 0
	v_mov_b64_e32 v[72:73], 0
	v_mov_b64_e32 v[74:75], 0
	v_mov_b64_e32 v[76:77], 0
	v_mov_b64_e32 v[78:79], 0
	v_mov_b64_e32 v[80:81], 0
	v_mov_b64_e32 v[82:83], 0
	v_mov_b64_e32 v[84:85], 0
	v_mov_b64_e32 v[86:87], 0
	v_mov_b64_e32 v[88:89], 0
	v_mov_b64_e32 v[90:91], 0
	v_mov_b64_e32 v[92:93], 0
	v_mov_b64_e32 v[94:95], 0
	v_mov_b64_e32 v[96:97], 0
	v_mov_b64_e32 v[98:99], 0
	v_mov_b64_e32 v[100:101], 0
	v_mov_b64_e32 v[102:103], 0
	v_mov_b64_e32 v[104:105], 0
	v_mov_b64_e32 v[106:107], 0
	v_mov_b64_e32 v[108:109], 0
	v_mov_b64_e32 v[110:111], 0
	v_mov_b64_e32 v[112:113], 0
	v_mov_b64_e32 v[114:115], 0
	v_mov_b64_e32 v[116:117], 0
	v_mov_b64_e32 v[118:119], 0
	v_mov_b64_e32 v[120:121], 0
	v_mov_b64_e32 v[122:123], 0
	v_mov_b64_e32 v[124:125], 0
	v_mov_b64_e32 v[126:127], 0
	s_andn2_b64 vcc, exec, s[20:21]
	s_waitcnt vmcnt(0)
	s_waitcnt lgkmcnt(0)
	.p2align 8
	s_cbranch_vccnz .LBB0_265
	s_add_u32 s40, s40, 0x80
	s_addc_u32 s41, s41, 0
	s_add_u32 s33, s42, 0x100
	s_addc_u32 s38, s43, 0
	s_mov_b32 s42, 0
	s_cmp_eq_u32 s87, 1
	s_cbranch_scc0 .Ltb_p1
	s_mov_b32 s87, 0
	s_barrier
; #define PG8_STAGE(bufoff, gbase, voff) do { _Pragma("unroll") for (int _i = 0; _i < 2; ++_i) \
;         __builtin_amdgcn_global_load_lds((const unsigned*)((const char*)(gbase) + (voff)[_i]), (PG8_LAS unsigned*)(lds + (bufoff) + ldsw + _i * 8192), 16, 0, 0); } while (0)
; #define PG8_LDA(dst, b, h) do { _Pragma("unroll") for (int m = 0; m < 4; ++m) _Pragma("unroll") for (int k = 0; k < 2; ++k) dst[m][k] = *(const PG8_LAS bf16x8*)(lds + PG8_SA(b, h) + aoff + m * 2048 + k * 1024); } while (0)
; #define PG8_LDB(dst, b, h) do { _Pragma("unroll") for (int n = 0; n < 2; ++n) _Pragma("unroll") for (int k = 0; k < 2; ++k) dst[n][k] = *(const PG8_LAS bf16x8*)(lds + PG8_SB(b, h) + boff + n * 2048 + k * 1024); } while (0)
; #define PG8_MMA(ai, bj, At, Bt) do { __builtin_amdgcn_s_setprio(1); _Pragma("unroll") for (int m = 0; m < 4; ++m) _Pragma("unroll") for (int n = 0; n < 2; ++n) _Pragma("unroll") for (int k = 0; k < 2; ++k) \
;         acc[ai][bj][m][n] = __builtin_amdgcn_mfma_f32_16x16x32_bf16(Bt[n][k], At[m][k], acc[ai][bj][m][n], 0, 0, 0); __builtin_amdgcn_s_setprio(0); } while (0)
; #define PG8_WAIT_V(n) asm volatile("s_waitcnt vmcnt(" #n ")" ::: "memory")
; #define PG8_WAIT_L(n) asm volatile("s_waitcnt lgkmcnt(" #n ")" ::: "memory")
; #define PG8_BAR __builtin_amdgcn_s_barrier()
; #define PG8_SCHED __builtin_amdgcn_sched_barrier(0)
; template <class Epi, class Sched, bool ALIGN_EPI = false, bool SP2 = false>
; __device__ __forceinline__ void gemm_phase(PG8_LAS unsigned char* lds, const Gemm g, const Sched& S, const Epi& E) {
;     ...
;             PG8_LDB(B0, 0, 0); PG8_LDB(B1, 0, 1); PG8_SCHED; PG8_LDA(At, 0, 0); PG8_STAGE(PG8_SA(1, 1), a1 + hstep, voffA);
;             PG8_WAIT_V(8); PG8_WAIT_L(0); PG8_BAR; PG8_MMA(0, 0, At, B0); PG8_MMA(0, 1, At, B1); PG8_BAR; PG8_SCHED;
;             PG8_LDA(At, 0, 1); PG8_STAGE(PG8_SB(0, 0), b2, voffB); PG8_STAGE(PG8_SB(0, 1), b2 + hstep, voffB); PG8_STAGE(PG8_SA(0, 0), a2, voffA);
;             PG8_WAIT_V(8); PG8_WAIT_L(0); PG8_BAR; PG8_MMA(1, 0, At, B0); PG8_MMA(1, 1, At, B1); PG8_BAR; PG8_SCHED;
.Ltb_p1:
.LBB0_264:
	ds_read_b128 v[148:151], v168
	ds_read_b128 v[152:155], v168 offset:1024
	ds_read_b128 v[156:159], v168 offset:2048
	ds_read_b128 v[160:163], v168 offset:3072
	ds_read_b128 v[174:177], v169
	ds_read_b128 v[178:181], v169 offset:1024
	ds_read_b128 v[182:185], v169 offset:2048
	ds_read_b128 v[186:189], v169 offset:3072
	s_add_i32 s71, s42, 2
	s_add_u32 s72, s40, 0x80
	s_addc_u32 s43, s41, 0
	s_cmp_eq_u32 s63, s42
	s_cselect_b32 s42, s8, s72
	s_cselect_b32 s43, s9, s43
	s_cselect_b32 s73, s37, s38
	s_cselect_b32 s72, s36, s33
	v_lshl_add_u64 v[164:165], s[40:41], 0, v[140:141]
	s_add_i32 m0, s56, 0xc000
	ds_read_b128 v[194:197], v170
	ds_read_b128 v[198:201], v170 offset:1024
	ds_read_b128 v[202:205], v170 offset:2048
	ds_read_b128 v[206:209], v170 offset:3072
	ds_read_b128 v[210:213], v170 offset:4096
	ds_read_b128 v[214:217], v170 offset:5120
	ds_read_b128 v[218:221], v170 offset:6144
	ds_read_b128 v[222:225], v170 offset:7168
	global_load_lds_dwordx4 v[164:165], off
	v_lshl_add_u64 v[164:165], s[40:41], 0, v[142:143]
	s_add_i32 m0, s56, 0xe000
	s_nop 0
	global_load_lds_dwordx4 v[164:165], off
	s_waitcnt vmcnt(8)
	s_waitcnt lgkmcnt(0)
	s_barrier
	s_setprio 1
	s_waitcnt lgkmcnt(0)
	v_mfma_f32_16x16x32_bf16 v[120:123], v[148:151], v[194:197], v[120:123]
	v_mfma_f32_16x16x32_bf16 v[116:119], v[156:159], v[194:197], v[116:119]
	v_mfma_f32_16x16x32_bf16 v[108:111], v[148:151], v[202:205], v[108:111]
	v_mfma_f32_16x16x32_bf16 v[100:103], v[156:159], v[202:205], v[100:103]
	v_mfma_f32_16x16x32_bf16 v[92:95], v[148:151], v[210:213], v[92:95]
	v_mfma_f32_16x16x32_bf16 v[84:87], v[156:159], v[210:213], v[84:87]
	v_mfma_f32_16x16x32_bf16 v[76:79], v[148:151], v[218:221], v[76:79]
	v_mfma_f32_16x16x32_bf16 v[68:71], v[156:159], v[218:221], v[68:71]
	v_mfma_f32_16x16x32_bf16 v[120:123], v[152:155], v[198:201], v[120:123]
	v_mfma_f32_16x16x32_bf16 v[116:119], v[160:163], v[198:201], v[116:119]
	v_mfma_f32_16x16x32_bf16 v[108:111], v[152:155], v[206:209], v[108:111]
	v_mfma_f32_16x16x32_bf16 v[100:103], v[160:163], v[206:209], v[100:103]
	v_mfma_f32_16x16x32_bf16 v[92:95], v[152:155], v[214:217], v[92:95]
	v_mfma_f32_16x16x32_bf16 v[84:87], v[160:163], v[214:217], v[84:87]
	v_mfma_f32_16x16x32_bf16 v[76:79], v[152:155], v[222:225], v[76:79]
	v_mfma_f32_16x16x32_bf16 v[68:71], v[160:163], v[222:225], v[68:71]
	s_setprio 0
	s_setprio 1
	v_mfma_f32_16x16x32_bf16 v[124:127], v[174:177], v[194:197], v[124:127]
	v_mfma_f32_16x16x32_bf16 v[112:115], v[182:185], v[194:197], v[112:115]
	v_mfma_f32_16x16x32_bf16 v[104:107], v[174:177], v[202:205], v[104:107]
	v_mfma_f32_16x16x32_bf16 v[96:99], v[182:185], v[202:205], v[96:99]
	v_mfma_f32_16x16x32_bf16 v[88:91], v[174:177], v[210:213], v[88:91]
	v_mfma_f32_16x16x32_bf16 v[80:83], v[182:185], v[210:213], v[80:83]
	v_mfma_f32_16x16x32_bf16 v[72:75], v[174:177], v[218:221], v[72:75]
	v_mfma_f32_16x16x32_bf16 v[64:67], v[182:185], v[218:221], v[64:67]
	v_mfma_f32_16x16x32_bf16 v[124:127], v[178:181], v[198:201], v[124:127]
	v_mfma_f32_16x16x32_bf16 v[112:115], v[186:189], v[198:201], v[112:115]
	v_mfma_f32_16x16x32_bf16 v[104:107], v[178:181], v[206:209], v[104:107]
	v_mfma_f32_16x16x32_bf16 v[96:99], v[186:189], v[206:209], v[96:99]
	v_mfma_f32_16x16x32_bf16 v[88:91], v[178:181], v[214:217], v[88:91]
	v_mfma_f32_16x16x32_bf16 v[80:83], v[186:189], v[214:217], v[80:83]
	v_mfma_f32_16x16x32_bf16 v[72:75], v[178:181], v[222:225], v[72:75]
	v_mfma_f32_16x16x32_bf16 v[64:67], v[186:189], v[222:225], v[64:67]
	s_setprio 0
	s_barrier
	s_add_i32 s74, s66, s3
	v_lshl_add_u64 v[164:165], s[72:73], 0, v[134:135]
	s_mov_b32 m0, s74
	ds_read_b128 v[194:197], v170 offset:16384
	ds_read_b128 v[198:201], v170 offset:17408
	ds_read_b128 v[202:205], v170 offset:18432
	ds_read_b128 v[206:209], v170 offset:19456
	ds_read_b128 v[210:213], v170 offset:20480
	ds_read_b128 v[214:217], v170 offset:21504
	ds_read_b128 v[218:221], v170 offset:22528
	ds_read_b128 v[222:225], v170 offset:23552
	global_load_lds_dwordx4 v[164:165], off
	s_add_i32 m0, s74, 0x2000
	v_lshl_add_u64 v[190:191], s[72:73], 0, v[130:131]
	s_add_u32 s72, s72, s12
	s_addc_u32 s73, s73, s13
	s_add_i32 s74, s67, s3
	global_load_lds_dwordx4 v[190:191], off
	v_lshl_add_u64 v[226:227], s[72:73], 0, v[134:135]
	s_mov_b32 m0, s74
	v_lshl_add_u64 v[228:229], s[72:73], 0, v[130:131]
	global_load_lds_dwordx4 v[226:227], off
	s_add_i32 m0, s74, 0x2000
	v_lshl_add_u64 v[230:231], s[42:43], 0, v[136:137]
	global_load_lds_dwordx4 v[228:229], off
	s_mov_b32 m0, s56
	v_lshl_add_u64 v[232:233], s[42:43], 0, v[132:133]
	global_load_lds_dwordx4 v[230:231], off
	s_mov_b32 m0, s57
	s_nop 0
	global_load_lds_dwordx4 v[232:233], off
	s_cmp_lg_u32 s71, 2
	s_cbranch_scc1 .Lss_p1_skip
	s_lshl_b32 s84, s4, 14
	s_mov_b32 s85, 0
	s_add_i32 m0, s56, 0x20000
	v_lshl_add_u64 v[238:239], v[236:237], 0, s[84:85]
	s_add_u32 s84, s84, 0x2000
	global_load_lds_dwordx4 v[238:239], off
	s_add_i32 m0, s56, 0x22000
	v_lshl_add_u64 v[238:239], v[236:237], 0, s[84:85]
	global_load_lds_dwordx4 v[238:239], off

; __device__ __forceinline__ unsigned cvt_pk_bf16(float lo, float hi) { unsigned r; asm volatile("v_cvt_pk_bf16_f32 %0, %1, %2" : "=v"(r) : "v"(lo), "v"(hi)); return r; }
; __device__ __forceinline__ float fast_rcp(float x) { return __builtin_amdgcn_rcpf(x); }
; __device__ __forceinline__ unsigned cvt_pk_bf16(float lo, float hi) { const f32x2 v = {lo, hi}; const bf16x2_t b = __builtin_convertvector(v, bf16x2_t); return __builtin_bit_cast(unsigned, b); }
;     __device__ __forceinline__ void operator()(const f32x4 (&acc)[2][2][4][2], const Unit& u, int wr, int wc, int fr, int fq) const {
;     ...
;                 const int r = row0 + ai * HALF + m * 16; const float rs = rsv[ai][m], nrs = rs * -1.4426950408889634f, rs2 = rs * rs;
;                 float o[8];
; #pragma unroll
;                 for (int n = 0; n < 2; ++n) {
;                     const f32x4 t = acc[ai][0][m][n] * nrs, p = (acc[ai][0][m][n] * acc[ai][1][m][n]) * rs2;
; #pragma unroll
;                     for (int j = 0; j < 4; ++j) o[4 * n + j] = p[j] * fast_rcp(1.0f + __builtin_amdgcn_exp2f(t[j]));
;                 }
;                 u32x4 w; w.x = cvt_pk_bf16(o[0], o[1]); w.y = cvt_pk_bf16(o[2], o[3]); w.z = cvt_pk_bf16(o[4], o[5]); w.w = cvt_pk_bf16(o[6], o[7]);
;                 *(u32x4*)(O + (size_t)r * ldo + col0) = w;
.Lrs_reuse_p1:
	v_pk_mul_f32 v[124:125], v[124:125], v[120:121]
	v_pk_mul_f32 v[126:127], v[126:127], v[122:123]
	v_pk_mul_f32 v[112:113], v[112:113], v[116:117]
	v_pk_mul_f32 v[114:115], v[114:115], v[118:119]
	v_pk_mul_f32 v[104:105], v[104:105], v[108:109]
	v_pk_mul_f32 v[106:107], v[106:107], v[110:111]
	v_pk_mul_f32 v[96:97], v[96:97], v[100:101]
	v_pk_mul_f32 v[98:99], v[98:99], v[102:103]
	v_pk_mul_f32 v[88:89], v[88:89], v[92:93]
	v_pk_mul_f32 v[90:91], v[90:91], v[94:95]
	v_pk_mul_f32 v[80:81], v[80:81], v[84:85]
	v_pk_mul_f32 v[82:83], v[82:83], v[86:87]
	v_pk_mul_f32 v[72:73], v[72:73], v[76:77]
	v_pk_mul_f32 v[74:75], v[74:75], v[78:79]
	v_pk_mul_f32 v[64:65], v[64:65], v[68:69]
	v_pk_mul_f32 v[66:67], v[66:67], v[70:71]
	v_pk_mul_f32 v[56:57], v[56:57], v[60:61]
	v_pk_mul_f32 v[58:59], v[58:59], v[62:63]
	v_pk_mul_f32 v[48:49], v[48:49], v[52:53]
	v_pk_mul_f32 v[50:51], v[50:51], v[54:55]
	v_pk_mul_f32 v[40:41], v[40:41], v[44:45]
	v_pk_mul_f32 v[42:43], v[42:43], v[46:47]
	v_pk_mul_f32 v[32:33], v[32:33], v[36:37]
	v_pk_mul_f32 v[34:35], v[34:35], v[38:39]
	v_pk_mul_f32 v[24:25], v[24:25], v[28:29]
	v_pk_mul_f32 v[26:27], v[26:27], v[30:31]
	v_pk_mul_f32 v[16:17], v[16:17], v[20:21]
	v_pk_mul_f32 v[18:19], v[18:19], v[22:23]
	v_pk_mul_f32 v[8:9], v[8:9], v[12:13]
	v_pk_mul_f32 v[10:11], v[10:11], v[14:15]
	v_pk_mul_f32 v[0:1], v[0:1], v[4:5]
	v_pk_mul_f32 v[2:3], v[2:3], v[6:7]
	v_mul_f32_e32 v230, 0xbfb8aa3b, v242
	v_mul_f32_e32 v231, v242, v242
	v_mul_f32_e32 v232, 0xbfb8aa3b, v243
	v_mul_f32_e32 v233, v243, v243
	v_mul_f32_e32 v234, 0xbfb8aa3b, v244
	v_mul_f32_e32 v235, v244, v244
	v_mul_f32_e32 v184, 0xbfb8aa3b, v245
	v_mul_f32_e32 v185, v245, v245
	v_mul_f32_e32 v186, 0xbfb8aa3b, v246
	v_mul_f32_e32 v187, v246, v246
	v_mul_f32_e32 v188, 0xbfb8aa3b, v247
	v_mul_f32_e32 v189, v247, v247
	v_mul_f32_e32 v190, 0xbfb8aa3b, v248
	v_mul_f32_e32 v191, v248, v248
	v_mul_f32_e32 v204, 0xbfb8aa3b, v249
	v_mul_f32_e32 v205, v249, v249
	v_pk_mul_f32 v[120:121], v[120:121], v[230:231] op_sel_hi:[1,0]
	v_pk_mul_f32 v[122:123], v[122:123], v[230:231] op_sel_hi:[1,0]
	v_pk_mul_f32 v[116:117], v[116:117], v[230:231] op_sel_hi:[1,0]
	v_pk_mul_f32 v[118:119], v[118:119], v[230:231] op_sel_hi:[1,0]
	v_exp_f32_e32 v120, v120
	v_exp_f32_e32 v121, v121
	v_exp_f32_e32 v122, v122
	v_exp_f32_e32 v123, v123
	v_exp_f32_e32 v116, v116
	v_exp_f32_e32 v117, v117
	v_exp_f32_e32 v118, v118
	v_exp_f32_e32 v119, v119
	v_pk_mul_f32 v[124:125], v[124:125], v[230:231] op_sel:[0,1] op_sel_hi:[1,1]
	v_pk_mul_f32 v[126:127], v[126:127], v[230:231] op_sel:[0,1] op_sel_hi:[1,1]
	v_pk_mul_f32 v[112:113], v[112:113], v[230:231] op_sel:[0,1] op_sel_hi:[1,1]
	v_pk_mul_f32 v[114:115], v[114:115], v[230:231] op_sel:[0,1] op_sel_hi:[1,1]
	v_pk_add_f32 v[120:121], v[120:121], 1.0 op_sel_hi:[1,0]
	v_pk_add_f32 v[122:123], v[122:123], 1.0 op_sel_hi:[1,0]
	v_pk_add_f32 v[116:117], v[116:117], 1.0 op_sel_hi:[1,0]
	v_pk_add_f32 v[118:119], v[118:119], 1.0 op_sel_hi:[1,0]
	v_rcp_f32_e32 v120, v120
	v_rcp_f32_e32 v121, v121
	v_rcp_f32_e32 v122, v122
	v_rcp_f32_e32 v123, v123
	v_rcp_f32_e32 v116, v116
	v_rcp_f32_e32 v117, v117
	v_rcp_f32_e32 v118, v118
	v_rcp_f32_e32 v119, v119
	v_mad_i64_i32 v[208:209], s[4:5], v162, s68, v[220:221]
	v_lshl_add_u64 v[208:209], v[208:209], 0, v[250:251]
	v_pk_mul_f32 v[124:125], v[124:125], v[120:121]
	v_pk_mul_f32 v[126:127], v[126:127], v[122:123]
	v_pk_mul_f32 v[112:113], v[112:113], v[116:117]
	v_pk_mul_f32 v[114:115], v[114:115], v[118:119]
	v_cvt_pk_bf16_f32 v120, v124, v125
	v_cvt_pk_bf16_f32 v121, v126, v127
	v_cvt_pk_bf16_f32 v122, v112, v113
	v_cvt_pk_bf16_f32 v123, v114, v115
	global_store_dwordx4 v[208:209], v[120:123], off
	v_pk_mul_f32 v[108:109], v[108:109], v[232:233] op_sel_hi:[1,0]
	v_pk_mul_f32 v[110:111], v[110:111], v[232:233] op_sel_hi:[1,0]
	v_pk_mul_f32 v[100:101], v[100:101], v[232:233] op_sel_hi:[1,0]
	v_pk_mul_f32 v[102:103], v[102:103], v[232:233] op_sel_hi:[1,0]
	v_exp_f32_e32 v108, v108
	v_exp_f32_e32 v109, v109
	v_exp_f32_e32 v110, v110
	v_exp_f32_e32 v111, v111
	v_exp_f32_e32 v100, v100
	v_exp_f32_e32 v101, v101
	v_exp_f32_e32 v102, v102
	v_exp_f32_e32 v103, v103
	v_pk_mul_f32 v[104:105], v[104:105], v[232:233] op_sel:[0,1] op_sel_hi:[1,1]
	v_pk_mul_f32 v[106:107], v[106:107], v[232:233] op_sel:[0,1] op_sel_hi:[1,1]
	v_pk_mul_f32 v[96:97], v[96:97], v[232:233] op_sel:[0,1] op_sel_hi:[1,1]
	v_pk_mul_f32 v[98:99], v[98:99], v[232:233] op_sel:[0,1] op_sel_hi:[1,1]
	v_pk_add_f32 v[108:109], v[108:109], 1.0 op_sel_hi:[1,0]
	v_pk_add_f32 v[110:111], v[110:111], 1.0 op_sel_hi:[1,0]
	v_pk_add_f32 v[100:101], v[100:101], 1.0 op_sel_hi:[1,0]
	v_pk_add_f32 v[102:103], v[102:103], 1.0 op_sel_hi:[1,0]
	v_rcp_f32_e32 v108, v108
	v_rcp_f32_e32 v109, v109
	v_rcp_f32_e32 v110, v110
	v_rcp_f32_e32 v111, v111
	v_rcp_f32_e32 v100, v100
	v_rcp_f32_e32 v101, v101
	v_rcp_f32_e32 v102, v102
	v_rcp_f32_e32 v103, v103
	v_mad_i64_i32 v[208:209], s[4:5], v160, s68, v[220:221]
	v_lshl_add_u64 v[208:209], v[208:209], 0, v[250:251]
	v_pk_mul_f32 v[104:105], v[104:105], v[108:109]
	v_pk_mul_f32 v[106:107], v[106:107], v[110:111]
	v_pk_mul_f32 v[96:97], v[96:97], v[100:101]
	v_pk_mul_f32 v[98:99], v[98:99], v[102:103]
	v_cvt_pk_bf16_f32 v108, v104, v105
	v_cvt_pk_bf16_f32 v109, v106, v107
	v_cvt_pk_bf16_f32 v110, v96, v97
	v_cvt_pk_bf16_f32 v111, v98, v99
	global_store_dwordx4 v[208:209], v[108:111], off
	v_pk_mul_f32 v[92:93], v[92:93], v[234:235] op_sel_hi:[1,0]
	v_pk_mul_f32 v[94:95], v[94:95], v[234:235] op_sel_hi:[1,0]
	v_pk_mul_f32 v[84:85], v[84:85], v[234:235] op_sel_hi:[1,0]
	v_pk_mul_f32 v[86:87], v[86:87], v[234:235] op_sel_hi:[1,0]
; __device__ __forceinline__ unsigned cvt_pk_bf16(float lo, float hi) { unsigned r; asm volatile("v_cvt_pk_bf16_f32 %0, %1, %2" : "=v"(r) : "v"(lo), "v"(hi)); return r; }
; __device__ __forceinline__ float fast_rcp(float x) { return __builtin_amdgcn_rcpf(x); }
; __device__ __forceinline__ unsigned cvt_pk_bf16(float lo, float hi) { const f32x2 v = {lo, hi}; const bf16x2_t b = __builtin_convertvector(v, bf16x2_t); return __builtin_bit_cast(unsigned, b); }
;     __device__ __forceinline__ void operator()(const f32x4 (&acc)[2][2][4][2], const Unit& u, int wr, int wc, int fr, int fq) const {
;     ...
;                 const int r = row0 + ai * HALF + m * 16; const float rs = rsv[ai][m], nrs = rs * -1.4426950408889634f, rs2 = rs * rs;
;                 float o[8];
; #pragma unroll
;                 for (int n = 0; n < 2; ++n) {
;                     const f32x4 t = acc[ai][0][m][n] * nrs, p = (acc[ai][0][m][n] * acc[ai][1][m][n]) * rs2;
; #pragma unroll
;                     for (int j = 0; j < 4; ++j) o[4 * n + j] = p[j] * fast_rcp(1.0f + __builtin_amdgcn_exp2f(t[j]));
;                 }
;                 u32x4 w; w.x = cvt_pk_bf16(o[0], o[1]); w.y = cvt_pk_bf16(o[2], o[3]); w.z = cvt_pk_bf16(o[4], o[5]); w.w = cvt_pk_bf16(o[6], o[7]);
;                 *(u32x4*)(O + (size_t)r * ldo + col0) = w;
	v_exp_f32_e32 v92, v92
	v_exp_f32_e32 v93, v93
	v_exp_f32_e32 v94, v94
	v_exp_f32_e32 v95, v95
	v_exp_f32_e32 v84, v84
	v_exp_f32_e32 v85, v85
	v_exp_f32_e32 v86, v86
	v_exp_f32_e32 v87, v87
	v_pk_mul_f32 v[88:89], v[88:89], v[234:235] op_sel:[0,1] op_sel_hi:[1,1]
	v_pk_mul_f32 v[90:91], v[90:91], v[234:235] op_sel:[0,1] op_sel_hi:[1,1]
	v_pk_mul_f32 v[80:81], v[80:81], v[234:235] op_sel:[0,1] op_sel_hi:[1,1]
	v_pk_mul_f32 v[82:83], v[82:83], v[234:235] op_sel:[0,1] op_sel_hi:[1,1]
	v_pk_add_f32 v[92:93], v[92:93], 1.0 op_sel_hi:[1,0]
	v_pk_add_f32 v[94:95], v[94:95], 1.0 op_sel_hi:[1,0]
	v_pk_add_f32 v[84:85], v[84:85], 1.0 op_sel_hi:[1,0]
	v_pk_add_f32 v[86:87], v[86:87], 1.0 op_sel_hi:[1,0]
	v_rcp_f32_e32 v92, v92
	v_rcp_f32_e32 v93, v93
	v_rcp_f32_e32 v94, v94
	v_rcp_f32_e32 v95, v95
	v_rcp_f32_e32 v84, v84
	v_rcp_f32_e32 v85, v85
	v_rcp_f32_e32 v86, v86
	v_rcp_f32_e32 v87, v87
	v_mad_i64_i32 v[208:209], s[4:5], v158, s68, v[220:221]
	v_lshl_add_u64 v[208:209], v[208:209], 0, v[250:251]
	v_pk_mul_f32 v[88:89], v[88:89], v[92:93]
	v_pk_mul_f32 v[90:91], v[90:91], v[94:95]
	v_pk_mul_f32 v[80:81], v[80:81], v[84:85]
	v_pk_mul_f32 v[82:83], v[82:83], v[86:87]
	v_cvt_pk_bf16_f32 v92, v88, v89
	v_cvt_pk_bf16_f32 v93, v90, v91
	v_cvt_pk_bf16_f32 v94, v80, v81
	v_cvt_pk_bf16_f32 v95, v82, v83
	global_store_dwordx4 v[208:209], v[92:95], off
	v_pk_mul_f32 v[76:77], v[76:77], v[184:185] op_sel_hi:[1,0]
	v_pk_mul_f32 v[78:79], v[78:79], v[184:185] op_sel_hi:[1,0]
	v_pk_mul_f32 v[68:69], v[68:69], v[184:185] op_sel_hi:[1,0]
	v_pk_mul_f32 v[70:71], v[70:71], v[184:185] op_sel_hi:[1,0]
	v_exp_f32_e32 v76, v76
	v_exp_f32_e32 v77, v77
	v_exp_f32_e32 v78, v78
	v_exp_f32_e32 v79, v79
	v_exp_f32_e32 v68, v68
	v_exp_f32_e32 v69, v69
	v_exp_f32_e32 v70, v70
	v_exp_f32_e32 v71, v71
	v_pk_mul_f32 v[72:73], v[72:73], v[184:185] op_sel:[0,1] op_sel_hi:[1,1]
	v_pk_mul_f32 v[74:75], v[74:75], v[184:185] op_sel:[0,1] op_sel_hi:[1,1]
	v_pk_mul_f32 v[64:65], v[64:65], v[184:185] op_sel:[0,1] op_sel_hi:[1,1]
	v_pk_mul_f32 v[66:67], v[66:67], v[184:185] op_sel:[0,1] op_sel_hi:[1,1]
	v_pk_add_f32 v[76:77], v[76:77], 1.0 op_sel_hi:[1,0]
	v_pk_add_f32 v[78:79], v[78:79], 1.0 op_sel_hi:[1,0]
	v_pk_add_f32 v[68:69], v[68:69], 1.0 op_sel_hi:[1,0]
	v_pk_add_f32 v[70:71], v[70:71], 1.0 op_sel_hi:[1,0]
	v_rcp_f32_e32 v76, v76
	v_rcp_f32_e32 v77, v77
	v_rcp_f32_e32 v78, v78
	v_rcp_f32_e32 v79, v79
	v_rcp_f32_e32 v68, v68
	v_rcp_f32_e32 v69, v69
	v_rcp_f32_e32 v70, v70
	v_rcp_f32_e32 v71, v71
	v_mad_i64_i32 v[208:209], s[4:5], v156, s68, v[220:221]
	v_lshl_add_u64 v[208:209], v[208:209], 0, v[250:251]
	v_pk_mul_f32 v[72:73], v[72:73], v[76:77]
	v_pk_mul_f32 v[74:75], v[74:75], v[78:79]
	v_pk_mul_f32 v[64:65], v[64:65], v[68:69]
	v_pk_mul_f32 v[66:67], v[66:67], v[70:71]
	v_cvt_pk_bf16_f32 v76, v72, v73
	v_cvt_pk_bf16_f32 v77, v74, v75
	v_cvt_pk_bf16_f32 v78, v64, v65
	v_cvt_pk_bf16_f32 v79, v66, v67
	global_store_dwordx4 v[208:209], v[76:79], off
	v_pk_mul_f32 v[60:61], v[60:61], v[186:187] op_sel_hi:[1,0]
	v_pk_mul_f32 v[62:63], v[62:63], v[186:187] op_sel_hi:[1,0]
	v_pk_mul_f32 v[52:53], v[52:53], v[186:187] op_sel_hi:[1,0]
	v_pk_mul_f32 v[54:55], v[54:55], v[186:187] op_sel_hi:[1,0]
	v_exp_f32_e32 v60, v60
	v_exp_f32_e32 v61, v61
	v_exp_f32_e32 v62, v62
	v_exp_f32_e32 v63, v63
	v_exp_f32_e32 v52, v52
	v_exp_f32_e32 v53, v53
	v_exp_f32_e32 v54, v54
	v_exp_f32_e32 v55, v55
	v_pk_mul_f32 v[56:57], v[56:57], v[186:187] op_sel:[0,1] op_sel_hi:[1,1]
	v_pk_mul_f32 v[58:59], v[58:59], v[186:187] op_sel:[0,1] op_sel_hi:[1,1]
	v_pk_mul_f32 v[48:49], v[48:49], v[186:187] op_sel:[0,1] op_sel_hi:[1,1]
	v_pk_mul_f32 v[50:51], v[50:51], v[186:187] op_sel:[0,1] op_sel_hi:[1,1]
	v_pk_add_f32 v[60:61], v[60:61], 1.0 op_sel_hi:[1,0]
	v_pk_add_f32 v[62:63], v[62:63], 1.0 op_sel_hi:[1,0]
	v_pk_add_f32 v[52:53], v[52:53], 1.0 op_sel_hi:[1,0]
	v_pk_add_f32 v[54:55], v[54:55], 1.0 op_sel_hi:[1,0]
	v_rcp_f32_e32 v60, v60
	v_rcp_f32_e32 v61, v61
	v_rcp_f32_e32 v62, v62
	v_rcp_f32_e32 v63, v63
	v_rcp_f32_e32 v52, v52
	v_rcp_f32_e32 v53, v53
	v_rcp_f32_e32 v54, v54
	v_rcp_f32_e32 v55, v55
	v_mad_i64_i32 v[208:209], s[4:5], v154, s68, v[220:221]
	v_lshl_add_u64 v[208:209], v[208:209], 0, v[250:251]
	v_pk_mul_f32 v[56:57], v[56:57], v[60:61]
	v_pk_mul_f32 v[58:59], v[58:59], v[62:63]
	v_pk_mul_f32 v[48:49], v[48:49], v[52:53]
	v_pk_mul_f32 v[50:51], v[50:51], v[54:55]
	v_cvt_pk_bf16_f32 v60, v56, v57
	v_cvt_pk_bf16_f32 v61, v58, v59
	v_cvt_pk_bf16_f32 v62, v48, v49
	v_cvt_pk_bf16_f32 v63, v50, v51
	global_store_dwordx4 v[208:209], v[60:63], off
	v_pk_mul_f32 v[44:45], v[44:45], v[188:189] op_sel_hi:[1,0]
	v_pk_mul_f32 v[46:47], v[46:47], v[188:189] op_sel_hi:[1,0]
; __device__ __forceinline__ unsigned cvt_pk_bf16(float lo, float hi) { unsigned r; asm volatile("v_cvt_pk_bf16_f32 %0, %1, %2" : "=v"(r) : "v"(lo), "v"(hi)); return r; }
; __device__ __forceinline__ float fast_rcp(float x) { return __builtin_amdgcn_rcpf(x); }
; #define PG8_BAR __builtin_amdgcn_s_barrier()
; __device__ __forceinline__ unsigned cvt_pk_bf16(float lo, float hi) { const f32x2 v = {lo, hi}; const bf16x2_t b = __builtin_convertvector(v, bf16x2_t); return __builtin_bit_cast(unsigned, b); }
;     __device__ __forceinline__ void operator()(const f32x4 (&acc)[2][2][4][2], const Unit& u, int wr, int wc, int fr, int fq) const {
;     ...
;                 const int r = row0 + ai * HALF + m * 16; const float rs = rsv[ai][m], nrs = rs * -1.4426950408889634f, rs2 = rs * rs;
;                 float o[8];
; #pragma unroll
;                 for (int n = 0; n < 2; ++n) {
;                     const f32x4 t = acc[ai][0][m][n] * nrs, p = (acc[ai][0][m][n] * acc[ai][1][m][n]) * rs2;
; #pragma unroll
;                     for (int j = 0; j < 4; ++j) o[4 * n + j] = p[j] * fast_rcp(1.0f + __builtin_amdgcn_exp2f(t[j]));
;                 }
;                 u32x4 w; w.x = cvt_pk_bf16(o[0], o[1]); w.y = cvt_pk_bf16(o[2], o[3]); w.z = cvt_pk_bf16(o[4], o[5]); w.w = cvt_pk_bf16(o[6], o[7]);
;                 *(u32x4*)(O + (size_t)r * ldo + col0) = w;
; template <class Epi, class Sched, bool ALIGN_EPI = false, bool SP2 = false>
; __device__ __forceinline__ void gemm_phase(PG8_LAS unsigned char* lds, const Gemm g, const Sched& S, const Epi& E) {
;     ...
;         if (!has_next) break;
; #pragma unroll
;         for (int a = 0; a < 2; ++a)
; #pragma unroll
;             for (int b = 0; b < 2; ++b)
; #pragma unroll
;                 for (int m = 0; m < 4; ++m)
; #pragma unroll
;                     for (int n = 0; n < 2; ++n) acc[a][b][m][n] = (f32x4){0.f, 0.f, 0.f, 0.f};
;         cur = nxt; cA = nA; cB = nB; ++ui;
;         if constexpr (ALIGN_EPI) { if (wr == 1) PG8_BAR; }
	v_pk_mul_f32 v[36:37], v[36:37], v[188:189] op_sel_hi:[1,0]
	v_pk_mul_f32 v[38:39], v[38:39], v[188:189] op_sel_hi:[1,0]
	v_exp_f32_e32 v44, v44
	v_exp_f32_e32 v45, v45
	v_exp_f32_e32 v46, v46
	v_exp_f32_e32 v47, v47
	v_exp_f32_e32 v36, v36
	v_exp_f32_e32 v37, v37
	v_exp_f32_e32 v38, v38
	v_exp_f32_e32 v39, v39
	v_pk_mul_f32 v[40:41], v[40:41], v[188:189] op_sel:[0,1] op_sel_hi:[1,1]
	v_pk_mul_f32 v[42:43], v[42:43], v[188:189] op_sel:[0,1] op_sel_hi:[1,1]
	v_pk_mul_f32 v[32:33], v[32:33], v[188:189] op_sel:[0,1] op_sel_hi:[1,1]
	v_pk_mul_f32 v[34:35], v[34:35], v[188:189] op_sel:[0,1] op_sel_hi:[1,1]
	v_pk_add_f32 v[44:45], v[44:45], 1.0 op_sel_hi:[1,0]
	v_pk_add_f32 v[46:47], v[46:47], 1.0 op_sel_hi:[1,0]
	v_pk_add_f32 v[36:37], v[36:37], 1.0 op_sel_hi:[1,0]
	v_pk_add_f32 v[38:39], v[38:39], 1.0 op_sel_hi:[1,0]
	v_rcp_f32_e32 v44, v44
	v_rcp_f32_e32 v45, v45
	v_rcp_f32_e32 v46, v46
	v_rcp_f32_e32 v47, v47
	v_rcp_f32_e32 v36, v36
	v_rcp_f32_e32 v37, v37
	v_rcp_f32_e32 v38, v38
	v_rcp_f32_e32 v39, v39
	v_mad_i64_i32 v[208:209], s[4:5], v152, s68, v[220:221]
	v_lshl_add_u64 v[208:209], v[208:209], 0, v[250:251]
	v_pk_mul_f32 v[40:41], v[40:41], v[44:45]
	v_pk_mul_f32 v[42:43], v[42:43], v[46:47]
	v_pk_mul_f32 v[32:33], v[32:33], v[36:37]
	v_pk_mul_f32 v[34:35], v[34:35], v[38:39]
	v_cvt_pk_bf16_f32 v44, v40, v41
	v_cvt_pk_bf16_f32 v45, v42, v43
	v_cvt_pk_bf16_f32 v46, v32, v33
	v_cvt_pk_bf16_f32 v47, v34, v35
	global_store_dwordx4 v[208:209], v[44:47], off
	v_pk_mul_f32 v[28:29], v[28:29], v[190:191] op_sel_hi:[1,0]
	v_pk_mul_f32 v[30:31], v[30:31], v[190:191] op_sel_hi:[1,0]
	v_pk_mul_f32 v[20:21], v[20:21], v[190:191] op_sel_hi:[1,0]
	v_pk_mul_f32 v[22:23], v[22:23], v[190:191] op_sel_hi:[1,0]
	v_exp_f32_e32 v28, v28
	v_exp_f32_e32 v29, v29
	v_exp_f32_e32 v30, v30
	v_exp_f32_e32 v31, v31
	v_exp_f32_e32 v20, v20
	v_exp_f32_e32 v21, v21
	v_exp_f32_e32 v22, v22
	v_exp_f32_e32 v23, v23
	v_pk_mul_f32 v[24:25], v[24:25], v[190:191] op_sel:[0,1] op_sel_hi:[1,1]
	v_pk_mul_f32 v[26:27], v[26:27], v[190:191] op_sel:[0,1] op_sel_hi:[1,1]
	v_pk_mul_f32 v[16:17], v[16:17], v[190:191] op_sel:[0,1] op_sel_hi:[1,1]
	v_pk_mul_f32 v[18:19], v[18:19], v[190:191] op_sel:[0,1] op_sel_hi:[1,1]
	v_pk_add_f32 v[28:29], v[28:29], 1.0 op_sel_hi:[1,0]
	v_pk_add_f32 v[30:31], v[30:31], 1.0 op_sel_hi:[1,0]
	v_pk_add_f32 v[20:21], v[20:21], 1.0 op_sel_hi:[1,0]
	v_pk_add_f32 v[22:23], v[22:23], 1.0 op_sel_hi:[1,0]
	v_rcp_f32_e32 v28, v28
	v_rcp_f32_e32 v29, v29
	v_rcp_f32_e32 v30, v30
	v_rcp_f32_e32 v31, v31
	v_rcp_f32_e32 v20, v20
	v_rcp_f32_e32 v21, v21
	v_rcp_f32_e32 v22, v22
	v_rcp_f32_e32 v23, v23
	v_mad_i64_i32 v[208:209], s[4:5], v150, s68, v[220:221]
	v_lshl_add_u64 v[208:209], v[208:209], 0, v[250:251]
	v_pk_mul_f32 v[24:25], v[24:25], v[28:29]
	v_pk_mul_f32 v[26:27], v[26:27], v[30:31]
	v_pk_mul_f32 v[16:17], v[16:17], v[20:21]
	v_pk_mul_f32 v[18:19], v[18:19], v[22:23]
	v_cvt_pk_bf16_f32 v28, v24, v25
	v_cvt_pk_bf16_f32 v29, v26, v27
	v_cvt_pk_bf16_f32 v30, v16, v17
	v_cvt_pk_bf16_f32 v31, v18, v19
	global_store_dwordx4 v[208:209], v[28:31], off
	v_pk_mul_f32 v[12:13], v[12:13], v[204:205] op_sel_hi:[1,0]
	v_pk_mul_f32 v[14:15], v[14:15], v[204:205] op_sel_hi:[1,0]
	v_pk_mul_f32 v[4:5], v[4:5], v[204:205] op_sel_hi:[1,0]
	v_pk_mul_f32 v[6:7], v[6:7], v[204:205] op_sel_hi:[1,0]
	v_exp_f32_e32 v12, v12
	v_exp_f32_e32 v13, v13
	v_exp_f32_e32 v14, v14
	v_exp_f32_e32 v15, v15
	v_exp_f32_e32 v4, v4
	v_exp_f32_e32 v5, v5
	v_exp_f32_e32 v6, v6
	v_exp_f32_e32 v7, v7
	v_pk_mul_f32 v[8:9], v[8:9], v[204:205] op_sel:[0,1] op_sel_hi:[1,1]
	v_pk_mul_f32 v[10:11], v[10:11], v[204:205] op_sel:[0,1] op_sel_hi:[1,1]
	v_pk_mul_f32 v[0:1], v[0:1], v[204:205] op_sel:[0,1] op_sel_hi:[1,1]
	v_pk_mul_f32 v[2:3], v[2:3], v[204:205] op_sel:[0,1] op_sel_hi:[1,1]
	v_pk_add_f32 v[12:13], v[12:13], 1.0 op_sel_hi:[1,0]
	v_pk_add_f32 v[14:15], v[14:15], 1.0 op_sel_hi:[1,0]
	v_pk_add_f32 v[4:5], v[4:5], 1.0 op_sel_hi:[1,0]
	v_pk_add_f32 v[6:7], v[6:7], 1.0 op_sel_hi:[1,0]
	v_rcp_f32_e32 v12, v12
	v_rcp_f32_e32 v13, v13
	v_rcp_f32_e32 v14, v14
	v_rcp_f32_e32 v15, v15
	v_rcp_f32_e32 v4, v4
	v_rcp_f32_e32 v5, v5
	v_rcp_f32_e32 v6, v6
	v_rcp_f32_e32 v7, v7
	v_mad_i64_i32 v[208:209], s[4:5], v148, s68, v[220:221]
	v_lshl_add_u64 v[208:209], v[208:209], 0, v[250:251]
	v_pk_mul_f32 v[8:9], v[8:9], v[12:13]
	v_pk_mul_f32 v[10:11], v[10:11], v[14:15]
	v_pk_mul_f32 v[0:1], v[0:1], v[4:5]
	v_pk_mul_f32 v[2:3], v[2:3], v[6:7]
	v_cvt_pk_bf16_f32 v12, v8, v9
	v_cvt_pk_bf16_f32 v13, v10, v11
	v_cvt_pk_bf16_f32 v14, v0, v1
	v_cvt_pk_bf16_f32 v15, v2, v3
	global_store_dwordx4 v[208:209], v[12:15], off
	s_cbranch_vccnz .LBB0_255
	s_andn2_b64 vcc, exec, s[16:17]
	s_cbranch_vccnz .LBB0_254
	s_mov_b32 s87, 1
	s_branch .LBB0_254

; #define PG8_BAR __builtin_amdgcn_s_barrier()
; template <class Epi, class Sched, bool ALIGN_EPI = false, bool SP2 = false>
; __device__ __forceinline__ void gemm_phase(PG8_LAS unsigned char* lds, const Gemm g, const Sched& S, const Epi& E) {
;     int tid_ = threadIdx.x; asm volatile("" : "+v"(tid_));
;     const int tid = tid_, wid = __builtin_amdgcn_readfirstlane(tid >> 6), lane = tid & 63, wr = wid >> 2, wc = wid & 3, fr = lane & 15, fq = lane >> 4;
;     int K_ = g.K; asm volatile("" : "+s"(K_));
;     const int K = K_, nt = K / BK;
;     unsigned voffA[2], voffB[2];
; #pragma unroll
;     for (int i = 0; i < 2; ++i) { int R, C; stage_rc(tid * 16 + i * 8192, R, C); const int Rb = Epi::PERM ? ((R & ~31) + perm32(R & 31)) : R;
;         voffA[i] = (unsigned)(R * K + C) * 2u; voffB[i] = (unsigned)(Rb * K + C) * 2u; }
;     const size_t kstep = (size_t)(BK * 2);
;     const size_t hstep = (size_t)HALF * K * 2;
;     const size_t tstep = 2 * hstep;
;     const unsigned ldsw = (unsigned)wid * 1024u;
;     const int aoff = lds_byte(wr * 64 + fr, fq * 8), boff = lds_byte(wc * 32 + fr, fq * 8);
;     ...
;     Unit cur, nxt; int ui = 0;
;     if (!S.next(0, cur)) return;
;     f32x4 acc[2][2][4][2];
; #pragma unroll
;     for (int a = 0; a < 2; ++a)
; #pragma unroll
;         for (int b = 0; b < 2; ++b)
; #pragma unroll
;             for (int m = 0; m < 4; ++m)
; #pragma unroll
;                 for (int n = 0; n < 2; ++n) acc[a][b][m][n] = (f32x4){0.f, 0.f, 0.f, 0.f};
;     bf16x8 At[4][2], B0[2][2], B1[2][2];
;     const char* cA = (const char*)g.A + (size_t)cur.pm * tstep; const char* cB = (const char*)g.Bt + (size_t)cur.pn * tstep;
;     S.a_ready(cur);
;     if constexpr (SP2) {
;         PG8_STAGE(PG8_SB(0, 0), cB, voffB); PG8_STAGE(PG8_SB(0, 1), cB + hstep, voffB); PG8_STAGE(PG8_SA(0, 0), cA, voffA); PG8_STAGE(PG8_SA(0, 1), cA + hstep, voffA);
;         if (wr == 1) PG8_BAR;
;         PG8_WAIT_V(2); PG8_BAR;
;         PG8_STAGE(PG8_SB(1, 0), cB + kstep, voffB); PG8_STAGE(PG8_SA(1, 0), cA + kstep, voffA); PG8_STAGE(PG8_SB(1, 1), cB + hstep + kstep, voffB);
;         PG8_WAIT_V(6); PG8_BAR;
;     } else {
;         PG8_STAGE(PG8_SB(0, 0), cB, voffB); PG8_STAGE(PG8_SA(0, 0), cA, voffA); PG8_STAGE(PG8_SB(0, 1), cB + hstep, voffB); PG8_STAGE(PG8_SA(0, 1), cA + hstep, voffA);
;         if (wr == 1) PG8_BAR;
;         PG8_WAIT_V(4); PG8_BAR;
.LBB0_999:
	s_cmp_lt_i32 s28, 7
	s_cselect_b64 s[4:5], -1, 0
	s_and_b64 s[8:9], s[4:5], s[0:1]
	s_andn2_b64 vcc, exec, s[8:9]
	s_cbranch_vccnz .LBB0_1041
	s_mov_b32 s86, -1
	s_mov_b32 s87, 0
	v_lshlrev_b32_e32 v236, 4, v192
	v_mov_b32_e32 v237, 0
	v_lshl_add_u64 v[236:237], s[44:45], 0, v[236:237]
	v_mov_b32_e32 v12, v192
	s_movk_i32 s0, 0x400
	v_readfirstlane_b32 s7, v12
	s_cmpk_gt_i32 s2, 0x5d7
	s_cbranch_scc1 .LBB0_1021
	v_lshlrev_b32_e32 v0, 4, v12
	v_add_u32_e32 v1, 0x2000, v0
	s_waitcnt lgkmcnt(0)
	v_ashrrev_i32_e32 v2, 31, v1
	v_lshrrev_b32_e32 v2, 22, v2
	v_add_u32_e32 v2, v1, v2
	v_ashrrev_i32_e32 v2, 10, v2
	v_mul_i32_i24_e32 v3, 0x400, v2
	v_sub_u32_e32 v1, v1, v3
	v_lshrrev_b32_e32 v3, 4, v1
	v_bitop3_b32 v1, v3, v1, 32 bitop3:0x6c
	v_ashrrev_i32_e32 v3, 31, v1
	v_lshrrev_b32_e32 v3, 26, v3
	v_add_u32_e32 v3, v1, v3
	v_lshlrev_b32_e32 v5, 3, v2
	v_ashrrev_i32_e32 v4, 6, v3
	v_and_b32_e32 v5, -16, v5
	v_lshlrev_b32_e32 v2, 5, v2
	v_add_u32_e32 v5, v4, v5
	v_and_b32_e32 v13, 32, v2
	v_and_b32_e32 v2, 0xc0, v3
	v_and_b32_e32 v4, 3, v4
	s_mov_b32 s4, 0x7fffffe0
	v_lshrrev_b32_e32 v6, 2, v5
	v_lshlrev_b32_e32 v7, 1, v5
	v_sub_u32_e32 v1, v1, v2
	v_mov_b32_e32 v2, 1
	v_and_or_b32 v4, v5, s4, v4
	v_and_b32_e32 v6, 4, v6
	v_and_b32_e32 v7, 24, v7
	v_ashrrev_i16_sdwa v1, v2, sext(v1) dst_sel:DWORD dst_unused:UNUSED_PAD src0_sel:DWORD src1_sel:BYTE_0
	v_or3_b32 v4, v4, v6, v7
	v_bfe_i32 v14, v1, 0, 16
	v_mul_lo_u32 v4, v4, s0
	v_add_u32_e32 v1, v13, v14
	v_mul_lo_u32 v15, v5, s0
	v_add_lshl_u32 v128, v4, v1, 1
	v_add_lshl_u32 v130, v1, v15, 1
	v_bfe_i32 v1, v12, 27, 1
	v_lshrrev_b32_e32 v1, 22, v1
	v_add_u32_e32 v1, v0, v1
	v_and_b32_e32 v1, 0xfffffc00, v1
	v_sub_u32_e32 v0, v0, v1
	v_lshrrev_b32_e32 v1, 4, v0
	v_ashrrev_i32_e32 v4, 31, v12
	v_bitop3_b32 v0, v1, v0, 32 bitop3:0x6c
	v_lshrrev_b32_e32 v4, 26, v4
	v_ashrrev_i32_e32 v1, 31, v0
	v_add_u32_e32 v4, v12, v4
	v_lshrrev_b32_e32 v1, 26, v1
	v_ashrrev_i32_e32 v4, 6, v4
	v_add_u32_e32 v1, v0, v1
	v_lshlrev_b32_e32 v5, 3, v4
	s_add_u32 s3, s26, 0x1600000
	v_ashrrev_i32_e32 v3, 6, v1
	v_and_b32_e32 v5, -16, v5
	s_addc_u32 s40, s27, 0
	v_add_u32_e32 v5, v3, v5
	v_and_b32_e32 v3, 3, v3
	s_ashr_i32 s42, s2, 31
	v_and_or_b32 v3, v5, s4, v3
	s_lshr_b32 s4, s42, 29
	s_add_i32 s4, s2, s4
	s_ashr_i32 s18, s7, 6
	s_ashr_i32 s1, s0, 31
	s_ashr_i32 s5, s4, 3
	s_and_b32 s4, s4, -8
	s_ashr_i32 s19, s7, 8
	s_lshl_b64 s[10:11], s[0:1], 8
	s_lshl_b64 s[12:13], s[0:1], 9
	s_lshl_b32 s41, s18, 10
	s_sub_i32 s4, s2, s4
	s_cmp_lt_i32 s4, 0
	s_movk_i32 s43, 0xbc
	s_cselect_b32 s6, s43, 0xbb
	s_mul_i32 s4, s4, s6
	s_add_i32 s4, s4, s5
	s_mul_hi_i32 s5, s4, 0x2e8ba2e9
	s_lshr_b32 s6, s5, 31
	s_ashr_i32 s5, s5, 5
	v_and_b32_e32 v1, 0xc0, v1
	s_add_i32 s5, s5, s6
	v_lshrrev_b32_e32 v6, 2, v5
	v_lshlrev_b32_e32 v7, 1, v5
	v_sub_u32_e32 v0, v0, v1
	s_lshl_b32 s14, s5, 3
	v_and_b32_e32 v6, 4, v6
	v_and_b32_e32 v7, 24, v7
	v_lshlrev_b32_e32 v4, 5, v4
	v_ashrrev_i16_sdwa v0, v2, sext(v0) dst_sel:DWORD dst_unused:UNUSED_PAD src0_sel:DWORD src1_sel:BYTE_0
	s_sub_i32 s6, 0x44, s14
	s_mulk_i32 s5, 0xb0
	v_or3_b32 v3, v3, v6, v7
	v_and_b32_e32 v16, 32, v4
	v_bfe_i32 v17, v0, 0, 16
	s_min_u32 s15, s6, 8
	s_sub_i32 s16, s4, s5
	v_mul_lo_u32 v3, v3, s0
	v_add_u32_e32 v0, v16, v17
	s_sext_i32_i16 s4, s16
	v_cvt_f32_ubyte0_e32 v2, s15
	v_add_lshl_u32 v132, v3, v0, 1
	v_cvt_f32_i32_e32 v1, s4
	v_rcp_iflag_f32_e32 v3, v2
	v_mul_lo_u32 v18, v5, s0
	v_add_lshl_u32 v134, v0, v18, 1
	s_ashr_i32 s4, s4, 30
	v_mul_f32_e32 v0, v1, v3
	v_trunc_f32_e32 v0, v0
	v_fma_f32 v1, -v0, v2, v1
	v_cvt_i32_f32_e32 v0, v0
	s_or_b32 s6, s4, 1
	v_cmp_ge_f32_e64 s[4:5], |v1|, v2
	s_and_b64 s[4:5], s[4:5], exec
	s_cselect_b32 s4, s6, 0
	v_readfirstlane_b32 s5, v0
	s_add_i32 s6, s5, s4
	s_mul_i32 s4, s6, s15
	s_sub_i32 s4, s16, s4
	s_sext_i32_i16 s4, s4
	s_add_i32 s4, s14, s4
	s_ashr_i32 s5, s4, 31
	s_mul_i32 s5, s12, s5
	s_mul_hi_u32 s14, s12, s4
	s_add_i32 s5, s14, s5
	s_lshr_b64 s[14:15], s[0:1], 23
	s_mul_i32 s15, s14, s4
	s_bfe_i64 s[16:17], s[6:7], 0x100000
	s_add_i32 s5, s5, s15
	s_mul_i32 s15, s12, s17
	s_mul_hi_u32 s17, s12, s16
	s_add_i32 s15, s17, s15
	s_mul_i32 s14, s14, s16
	s_add_i32 s15, s15, s14
	s_mul_i32 s14, s12, s16
	s_add_u32 s38, s3, s14
	s_addc_u32 s39, s40, s15
	s_add_i32 s48, s41, 0
	s_add_i32 m0, s48, 0x10000
	s_mul_i32 s20, s12, s4
	global_load_lds_dwordx4 v132, s[38:39]
	s_add_i32 m0, s48, 0x12000
	s_add_u32 s14, s38, s10
	global_load_lds_dwordx4 v128, s[38:39]
	s_addc_u32 s15, s39, s11
	s_add_i32 m0, s48, 0x14000
	v_mov_b32_e32 v133, 0
	global_load_lds_dwordx4 v132, s[14:15]
	s_add_i32 m0, s48, 0x16000
	s_add_u32 s36, s34, s20
	s_addc_u32 s37, s35, s5
	s_add_i32 s49, s48, 0x2000
	global_load_lds_dwordx4 v128, s[14:15]
	s_mov_b32 m0, s48
	s_add_u32 s16, s36, s10
	global_load_lds_dwordx4 v134, s[36:37]
	s_mov_b32 m0, s49
	s_addc_u32 s17, s37, s11
	s_add_i32 s56, s48, 0x4000
	global_load_lds_dwordx4 v130, s[36:37]
	s_mov_b32 m0, s56
	s_add_i32 s57, s48, 0x6000
	global_load_lds_dwordx4 v134, s[16:17]
	s_mov_b32 m0, s57
	v_mov_b32_e32 v129, v133
	global_load_lds_dwordx4 v130, s[16:17]
	v_mov_b32_e32 v135, v133
	v_mov_b32_e32 v131, v133
	s_cmp_eq_u32 s19, 1
	s_mov_b32 s58, 0
	v_lshl_add_u64 v[8:9], s[38:39], 0, v[132:133]
	v_lshl_add_u64 v[4:5], s[38:39], 0, v[128:129]
	v_lshl_add_u64 v[2:3], s[14:15], 0, v[132:133]
	v_lshl_add_u64 v[0:1], s[14:15], 0, v[128:129]
	v_lshl_add_u64 v[6:7], s[36:37], 0, v[134:135]
	s_cselect_b64 s[14:15], -1, 0
	s_cmp_lg_u32 s19, 1
	v_lshl_add_u64 v[10:11], s[36:37], 0, v[130:131]
	s_cbranch_scc1 .LBB0_1003
	s_barrier

; template <class Epi, class Sched, bool ALIGN_EPI = false, bool SP2 = false>
; __device__ __forceinline__ void gemm_phase(PG8_LAS unsigned char* lds, const Gemm g, const Sched& S, const Epi& E) {
;     ...
;         for (int t = 0; t < nt; t += 2) {
;             const bool last = (t == nt - 2);
;             const char* a1 = cA + (size_t)(t + 1) * kstep;
;             const char* a2 = last ? nA : cA + (size_t)(t + 2) * kstep; const char* b2 = last ? nB : cB + (size_t)(t + 2) * kstep;
;             const char* a3 = a2 + kstep; const char* b3 = b2 + kstep;
;     ...
; #pragma unroll
;         for (int a = 0; a < 2; ++a)
; #pragma unroll
;             for (int b = 0; b < 2; ++b)
; #pragma unroll
;                 for (int m = 0; m < 4; ++m)
; #pragma unroll
;                     for (int n = 0; n < 2; ++n) acc[a][b][m][n] = (f32x4){0.f, 0.f, 0.f, 0.f};
;         cur = nxt; cA = nA; cB = nB; ++ui;
.LBB0_1012:
	v_mov_b64_e32 v[0:1], 0
	v_mov_b64_e32 v[2:3], 0
	v_mov_b64_e32 v[4:5], 0
	v_mov_b64_e32 v[6:7], 0
	v_mov_b64_e32 v[8:9], 0
	v_mov_b64_e32 v[10:11], 0
	v_mov_b64_e32 v[12:13], 0
	v_mov_b64_e32 v[14:15], 0
	v_mov_b64_e32 v[16:17], 0
	v_mov_b64_e32 v[18:19], 0
	v_mov_b64_e32 v[20:21], 0
	v_mov_b64_e32 v[22:23], 0
	v_mov_b64_e32 v[24:25], 0
	v_mov_b64_e32 v[26:27], 0
	v_mov_b64_e32 v[28:29], 0
	v_mov_b64_e32 v[30:31], 0
	v_mov_b64_e32 v[32:33], 0
	v_mov_b64_e32 v[34:35], 0
	v_mov_b64_e32 v[36:37], 0
	v_mov_b64_e32 v[38:39], 0
	v_mov_b64_e32 v[40:41], 0
	v_mov_b64_e32 v[42:43], 0
	v_mov_b64_e32 v[44:45], 0
	v_mov_b64_e32 v[46:47], 0
	v_mov_b64_e32 v[48:49], 0
	v_mov_b64_e32 v[50:51], 0
	v_mov_b64_e32 v[52:53], 0
	v_mov_b64_e32 v[54:55], 0
	v_mov_b64_e32 v[56:57], 0
	v_mov_b64_e32 v[58:59], 0
	v_mov_b64_e32 v[60:61], 0
	v_mov_b64_e32 v[62:63], 0
	v_mov_b64_e32 v[64:65], 0
	v_mov_b64_e32 v[66:67], 0
	v_mov_b64_e32 v[68:69], 0
	v_mov_b64_e32 v[70:71], 0
	v_mov_b64_e32 v[72:73], 0
	v_mov_b64_e32 v[74:75], 0
	v_mov_b64_e32 v[76:77], 0
	v_mov_b64_e32 v[78:79], 0
	v_mov_b64_e32 v[80:81], 0
	v_mov_b64_e32 v[82:83], 0
	v_mov_b64_e32 v[84:85], 0
	v_mov_b64_e32 v[86:87], 0
	v_mov_b64_e32 v[88:89], 0
	v_mov_b64_e32 v[90:91], 0
	v_mov_b64_e32 v[92:93], 0
	v_mov_b64_e32 v[94:95], 0
	v_mov_b64_e32 v[96:97], 0
	v_mov_b64_e32 v[98:99], 0
	v_mov_b64_e32 v[100:101], 0
	v_mov_b64_e32 v[102:103], 0
	v_mov_b64_e32 v[104:105], 0
	v_mov_b64_e32 v[106:107], 0
	v_mov_b64_e32 v[108:109], 0
	v_mov_b64_e32 v[110:111], 0
	v_mov_b64_e32 v[112:113], 0
	v_mov_b64_e32 v[114:115], 0
	v_mov_b64_e32 v[116:117], 0
	v_mov_b64_e32 v[118:119], 0
	v_mov_b64_e32 v[120:121], 0
	v_mov_b64_e32 v[122:123], 0
	v_mov_b64_e32 v[124:125], 0
	v_mov_b64_e32 v[126:127], 0
	s_andn2_b64 vcc, exec, s[18:19]
	s_waitcnt vmcnt(0)
	.p2align 8
	s_cbranch_vccnz .LBB0_1015
	s_add_u32 s36, s36, 0x80
	s_addc_u32 s37, s37, 0
	s_add_u32 s33, s38, 0x100
	s_addc_u32 s70, s39, 0
	s_mov_b32 s38, 0
	s_cmp_eq_u32 s87, 1
	s_cbranch_scc0 .Ltb_p6
	s_mov_b32 s87, 0
	s_barrier
; #define PG8_STAGE(bufoff, gbase, voff) do { _Pragma("unroll") for (int _i = 0; _i < 2; ++_i) \
;         __builtin_amdgcn_global_load_lds((const unsigned*)((const char*)(gbase) + (voff)[_i]), (PG8_LAS unsigned*)(lds + (bufoff) + ldsw + _i * 8192), 16, 0, 0); } while (0)
; #define PG8_LDA(dst, b, h) do { _Pragma("unroll") for (int m = 0; m < 4; ++m) _Pragma("unroll") for (int k = 0; k < 2; ++k) dst[m][k] = *(const PG8_LAS bf16x8*)(lds + PG8_SA(b, h) + aoff + m * 2048 + k * 1024); } while (0)
; #define PG8_LDB(dst, b, h) do { _Pragma("unroll") for (int n = 0; n < 2; ++n) _Pragma("unroll") for (int k = 0; k < 2; ++k) dst[n][k] = *(const PG8_LAS bf16x8*)(lds + PG8_SB(b, h) + boff + n * 2048 + k * 1024); } while (0)
; #define PG8_MMA(ai, bj, At, Bt) do { __builtin_amdgcn_s_setprio(1); _Pragma("unroll") for (int m = 0; m < 4; ++m) _Pragma("unroll") for (int n = 0; n < 2; ++n) _Pragma("unroll") for (int k = 0; k < 2; ++k) \
;         acc[ai][bj][m][n] = __builtin_amdgcn_mfma_f32_16x16x32_bf16(Bt[n][k], At[m][k], acc[ai][bj][m][n], 0, 0, 0); __builtin_amdgcn_s_setprio(0); } while (0)
; #define PG8_WAIT_V(n) asm volatile("s_waitcnt vmcnt(" #n ")" ::: "memory")
; #define PG8_WAIT_L(n) asm volatile("s_waitcnt lgkmcnt(" #n ")" ::: "memory")
; #define PG8_BAR __builtin_amdgcn_s_barrier()
; #define PG8_SCHED __builtin_amdgcn_sched_barrier(0)
; template <class Epi, class Sched, bool ALIGN_EPI = false, bool SP2 = false>
; __device__ __forceinline__ void gemm_phase(PG8_LAS unsigned char* lds, const Gemm g, const Sched& S, const Epi& E) {
;     ...
;             PG8_LDB(B0, 0, 0); PG8_LDB(B1, 0, 1); PG8_SCHED; PG8_LDA(At, 0, 0); PG8_STAGE(PG8_SA(1, 1), a1 + hstep, voffA);
;             PG8_WAIT_V(8); PG8_WAIT_L(0); PG8_BAR; PG8_MMA(0, 0, At, B0); PG8_MMA(0, 1, At, B1); PG8_BAR; PG8_SCHED;
;             PG8_LDA(At, 0, 1); PG8_STAGE(PG8_SB(0, 0), b2, voffB); PG8_STAGE(PG8_SB(0, 1), b2 + hstep, voffB); PG8_STAGE(PG8_SA(0, 0), a2, voffA);
;             PG8_WAIT_V(8); PG8_WAIT_L(0); PG8_BAR; PG8_MMA(1, 0, At, B0); PG8_MMA(1, 1, At, B1); PG8_BAR; PG8_SCHED;
.Ltb_p6:
.LBB0_1014:
	ds_read_b128 v[146:149], v167
	ds_read_b128 v[150:153], v167 offset:1024
	ds_read_b128 v[154:157], v167 offset:2048
	ds_read_b128 v[158:161], v167 offset:3072
	ds_read_b128 v[172:175], v168
	ds_read_b128 v[176:179], v168 offset:1024
	ds_read_b128 v[180:183], v168 offset:2048
	ds_read_b128 v[184:187], v168 offset:3072
	s_add_i32 s71, s38, 2
	s_add_u32 s72, s36, 0x80
	s_addc_u32 s39, s37, 0
	s_cmp_eq_u32 s62, s38
	s_cselect_b32 s38, s6, s72
	s_cselect_b32 s39, s7, s39
	s_cselect_b32 s73, s23, s70
	s_cselect_b32 s72, s22, s33
	v_lshl_add_u64 v[162:163], s[36:37], 0, v[138:139]
	s_add_i32 m0, s48, 0xc000
	ds_read_b128 v[188:191], v169
	ds_read_b128 v[194:197], v169 offset:1024
	ds_read_b128 v[198:201], v169 offset:2048
	ds_read_b128 v[202:205], v169 offset:3072
	ds_read_b128 v[206:209], v169 offset:4096
	ds_read_b128 v[210:213], v169 offset:5120
	ds_read_b128 v[214:217], v169 offset:6144
	ds_read_b128 v[218:221], v169 offset:7168
	global_load_lds_dwordx4 v[162:163], off
	v_lshl_add_u64 v[162:163], s[36:37], 0, v[140:141]
	s_add_i32 m0, s48, 0xe000
	s_nop 0
	global_load_lds_dwordx4 v[162:163], off
	s_waitcnt vmcnt(8)
	s_waitcnt lgkmcnt(0)
	s_barrier
	s_setprio 1
	s_waitcnt lgkmcnt(0)
	v_mfma_f32_16x16x32_bf16 v[120:123], v[146:149], v[188:191], v[120:123]
	v_mfma_f32_16x16x32_bf16 v[116:119], v[154:157], v[188:191], v[116:119]
	v_mfma_f32_16x16x32_bf16 v[108:111], v[146:149], v[198:201], v[108:111]
	v_mfma_f32_16x16x32_bf16 v[100:103], v[154:157], v[198:201], v[100:103]
	v_mfma_f32_16x16x32_bf16 v[92:95], v[146:149], v[206:209], v[92:95]
	v_mfma_f32_16x16x32_bf16 v[84:87], v[154:157], v[206:209], v[84:87]
	v_mfma_f32_16x16x32_bf16 v[76:79], v[146:149], v[214:217], v[76:79]
	v_mfma_f32_16x16x32_bf16 v[68:71], v[154:157], v[214:217], v[68:71]
	v_mfma_f32_16x16x32_bf16 v[120:123], v[150:153], v[194:197], v[120:123]
	v_mfma_f32_16x16x32_bf16 v[116:119], v[158:161], v[194:197], v[116:119]
	v_mfma_f32_16x16x32_bf16 v[108:111], v[150:153], v[202:205], v[108:111]
	v_mfma_f32_16x16x32_bf16 v[100:103], v[158:161], v[202:205], v[100:103]
	v_mfma_f32_16x16x32_bf16 v[92:95], v[150:153], v[210:213], v[92:95]
	v_mfma_f32_16x16x32_bf16 v[84:87], v[158:161], v[210:213], v[84:87]
	v_mfma_f32_16x16x32_bf16 v[76:79], v[150:153], v[218:221], v[76:79]
	v_mfma_f32_16x16x32_bf16 v[68:71], v[158:161], v[218:221], v[68:71]
	s_setprio 0
	s_setprio 1
	v_mfma_f32_16x16x32_bf16 v[124:127], v[172:175], v[188:191], v[124:127]
	v_mfma_f32_16x16x32_bf16 v[112:115], v[180:183], v[188:191], v[112:115]
	v_mfma_f32_16x16x32_bf16 v[104:107], v[172:175], v[198:201], v[104:107]
	v_mfma_f32_16x16x32_bf16 v[96:99], v[180:183], v[198:201], v[96:99]
	v_mfma_f32_16x16x32_bf16 v[88:91], v[172:175], v[206:209], v[88:91]
	v_mfma_f32_16x16x32_bf16 v[80:83], v[180:183], v[206:209], v[80:83]
	v_mfma_f32_16x16x32_bf16 v[72:75], v[172:175], v[214:217], v[72:75]
	v_mfma_f32_16x16x32_bf16 v[64:67], v[180:183], v[214:217], v[64:67]
	v_mfma_f32_16x16x32_bf16 v[124:127], v[176:179], v[194:197], v[124:127]
	v_mfma_f32_16x16x32_bf16 v[112:115], v[184:187], v[194:197], v[112:115]
	v_mfma_f32_16x16x32_bf16 v[104:107], v[176:179], v[202:205], v[104:107]
	v_mfma_f32_16x16x32_bf16 v[96:99], v[184:187], v[202:205], v[96:99]
	v_mfma_f32_16x16x32_bf16 v[88:91], v[176:179], v[210:213], v[88:91]
	v_mfma_f32_16x16x32_bf16 v[80:83], v[184:187], v[210:213], v[80:83]
	v_mfma_f32_16x16x32_bf16 v[72:75], v[176:179], v[218:221], v[72:75]
	v_mfma_f32_16x16x32_bf16 v[64:67], v[184:187], v[218:221], v[64:67]
	s_setprio 0
	s_barrier
	s_add_i32 s74, s65, s41
	v_lshl_add_u64 v[162:163], s[72:73], 0, v[132:133]
	s_mov_b32 m0, s74
	ds_read_b128 v[188:191], v169 offset:16384
	ds_read_b128 v[194:197], v169 offset:17408
	ds_read_b128 v[198:201], v169 offset:18432
	ds_read_b128 v[202:205], v169 offset:19456
	ds_read_b128 v[206:209], v169 offset:20480
	ds_read_b128 v[210:213], v169 offset:21504
	ds_read_b128 v[214:217], v169 offset:22528
	ds_read_b128 v[218:221], v169 offset:23552
	global_load_lds_dwordx4 v[162:163], off
	s_add_i32 m0, s74, 0x2000
	v_lshl_add_u64 v[222:223], s[72:73], 0, v[128:129]
	s_add_u32 s72, s72, s10
	s_addc_u32 s73, s73, s11
	s_add_i32 s74, s66, s41
	global_load_lds_dwordx4 v[222:223], off
	v_lshl_add_u64 v[224:225], s[72:73], 0, v[132:133]
	s_mov_b32 m0, s74
	v_lshl_add_u64 v[226:227], s[72:73], 0, v[128:129]
	global_load_lds_dwordx4 v[224:225], off
	s_add_i32 m0, s74, 0x2000
	v_lshl_add_u64 v[228:229], s[38:39], 0, v[134:135]
	global_load_lds_dwordx4 v[226:227], off
	s_mov_b32 m0, s48
	v_lshl_add_u64 v[230:231], s[38:39], 0, v[130:131]
	global_load_lds_dwordx4 v[228:229], off
	s_mov_b32 m0, s49
	s_nop 0
	global_load_lds_dwordx4 v[230:231], off
	s_cmp_lg_u32 s71, 2
	s_cbranch_scc1 .Lss_p6_skip
	s_lshl_b32 s84, s4, 14
	s_mov_b32 s85, 0
	s_add_i32 m0, s48, 0x20000
	v_lshl_add_u64 v[238:239], v[236:237], 0, s[84:85]
	s_add_u32 s84, s84, 0x2000
	global_load_lds_dwordx4 v[238:239], off
	s_add_i32 m0, s48, 0x22000
	v_lshl_add_u64 v[238:239], v[236:237], 0, s[84:85]
	global_load_lds_dwordx4 v[238:239], off

; __device__ __forceinline__ unsigned cvt_pk_bf16(float lo, float hi) { unsigned r; asm volatile("v_cvt_pk_bf16_f32 %0, %1, %2" : "=v"(r) : "v"(lo), "v"(hi)); return r; }
; __device__ __forceinline__ float fast_rcp(float x) { return __builtin_amdgcn_rcpf(x); }
; __device__ __forceinline__ unsigned cvt_pk_bf16(float lo, float hi) { const f32x2 v = {lo, hi}; const bf16x2_t b = __builtin_convertvector(v, bf16x2_t); return __builtin_bit_cast(unsigned, b); }
;     __device__ __forceinline__ void operator()(const f32x4 (&acc)[2][2][4][2], const Unit& u, int wr, int wc, int fr, int fq) const {
;     ...
;                 const int r = row0 + ai * HALF + m * 16; const float rs = rsv[ai][m], nrs = rs * -1.4426950408889634f, rs2 = rs * rs;
;                 float o[8];
; #pragma unroll
;                 for (int n = 0; n < 2; ++n) {
;                     const f32x4 t = acc[ai][0][m][n] * nrs, p = (acc[ai][0][m][n] * acc[ai][1][m][n]) * rs2;
; #pragma unroll
;                     for (int j = 0; j < 4; ++j) o[4 * n + j] = p[j] * fast_rcp(1.0f + __builtin_amdgcn_exp2f(t[j]));
;                 }
;                 u32x4 w; w.x = cvt_pk_bf16(o[0], o[1]); w.y = cvt_pk_bf16(o[2], o[3]); w.z = cvt_pk_bf16(o[4], o[5]); w.w = cvt_pk_bf16(o[6], o[7]);
;                 *(u32x4*)(O + (size_t)r * ldo + col0) = w;
.Lrs_reuse_p6:
	v_pk_mul_f32 v[124:125], v[124:125], v[120:121]
	v_pk_mul_f32 v[126:127], v[126:127], v[122:123]
	v_pk_mul_f32 v[112:113], v[112:113], v[116:117]
	v_pk_mul_f32 v[114:115], v[114:115], v[118:119]
	v_pk_mul_f32 v[104:105], v[104:105], v[108:109]
	v_pk_mul_f32 v[106:107], v[106:107], v[110:111]
	v_pk_mul_f32 v[96:97], v[96:97], v[100:101]
	v_pk_mul_f32 v[98:99], v[98:99], v[102:103]
	v_pk_mul_f32 v[88:89], v[88:89], v[92:93]
	v_pk_mul_f32 v[90:91], v[90:91], v[94:95]
	v_pk_mul_f32 v[80:81], v[80:81], v[84:85]
	v_pk_mul_f32 v[82:83], v[82:83], v[86:87]
	v_pk_mul_f32 v[72:73], v[72:73], v[76:77]
	v_pk_mul_f32 v[74:75], v[74:75], v[78:79]
	v_pk_mul_f32 v[64:65], v[64:65], v[68:69]
	v_pk_mul_f32 v[66:67], v[66:67], v[70:71]
	v_pk_mul_f32 v[56:57], v[56:57], v[60:61]
	v_pk_mul_f32 v[58:59], v[58:59], v[62:63]
	v_pk_mul_f32 v[48:49], v[48:49], v[52:53]
	v_pk_mul_f32 v[50:51], v[50:51], v[54:55]
	v_pk_mul_f32 v[40:41], v[40:41], v[44:45]
	v_pk_mul_f32 v[42:43], v[42:43], v[46:47]
	v_pk_mul_f32 v[32:33], v[32:33], v[36:37]
	v_pk_mul_f32 v[34:35], v[34:35], v[38:39]
	v_pk_mul_f32 v[24:25], v[24:25], v[28:29]
	v_pk_mul_f32 v[26:27], v[26:27], v[30:31]
	v_pk_mul_f32 v[16:17], v[16:17], v[20:21]
	v_pk_mul_f32 v[18:19], v[18:19], v[22:23]
	v_pk_mul_f32 v[8:9], v[8:9], v[12:13]
	v_pk_mul_f32 v[10:11], v[10:11], v[14:15]
	v_pk_mul_f32 v[0:1], v[0:1], v[4:5]
	v_pk_mul_f32 v[2:3], v[2:3], v[6:7]
	v_mul_f32_e32 v230, 0xbfb8aa3b, v242
	v_mul_f32_e32 v231, v242, v242
	v_mul_f32_e32 v232, 0xbfb8aa3b, v243
	v_mul_f32_e32 v233, v243, v243
	v_mul_f32_e32 v234, 0xbfb8aa3b, v244
	v_mul_f32_e32 v235, v244, v244
	v_mul_f32_e32 v184, 0xbfb8aa3b, v245
	v_mul_f32_e32 v185, v245, v245
	v_mul_f32_e32 v186, 0xbfb8aa3b, v246
	v_mul_f32_e32 v187, v246, v246
	v_mul_f32_e32 v188, 0xbfb8aa3b, v247
	v_mul_f32_e32 v189, v247, v247
	v_mul_f32_e32 v190, 0xbfb8aa3b, v248
	v_mul_f32_e32 v191, v248, v248
	v_mul_f32_e32 v204, 0xbfb8aa3b, v249
	v_mul_f32_e32 v205, v249, v249
	v_pk_mul_f32 v[120:121], v[120:121], v[230:231] op_sel_hi:[1,0]
	v_pk_mul_f32 v[122:123], v[122:123], v[230:231] op_sel_hi:[1,0]
	v_pk_mul_f32 v[116:117], v[116:117], v[230:231] op_sel_hi:[1,0]
	v_pk_mul_f32 v[118:119], v[118:119], v[230:231] op_sel_hi:[1,0]
	v_exp_f32_e32 v120, v120
	v_exp_f32_e32 v121, v121
	v_exp_f32_e32 v122, v122
	v_exp_f32_e32 v123, v123
	v_exp_f32_e32 v116, v116
	v_exp_f32_e32 v117, v117
	v_exp_f32_e32 v118, v118
	v_exp_f32_e32 v119, v119
	v_pk_mul_f32 v[124:125], v[124:125], v[230:231] op_sel:[0,1] op_sel_hi:[1,1]
	v_pk_mul_f32 v[126:127], v[126:127], v[230:231] op_sel:[0,1] op_sel_hi:[1,1]
	v_pk_mul_f32 v[112:113], v[112:113], v[230:231] op_sel:[0,1] op_sel_hi:[1,1]
	v_pk_mul_f32 v[114:115], v[114:115], v[230:231] op_sel:[0,1] op_sel_hi:[1,1]
	v_pk_add_f32 v[120:121], v[120:121], 1.0 op_sel_hi:[1,0]
	v_pk_add_f32 v[122:123], v[122:123], 1.0 op_sel_hi:[1,0]
	v_pk_add_f32 v[116:117], v[116:117], 1.0 op_sel_hi:[1,0]
	v_pk_add_f32 v[118:119], v[118:119], 1.0 op_sel_hi:[1,0]
	v_rcp_f32_e32 v120, v120
	v_rcp_f32_e32 v121, v121
	v_rcp_f32_e32 v122, v122
	v_rcp_f32_e32 v123, v123
	v_rcp_f32_e32 v116, v116
	v_rcp_f32_e32 v117, v117
	v_rcp_f32_e32 v118, v118
	v_rcp_f32_e32 v119, v119
	v_mad_i64_i32 v[208:209], s[4:5], v162, s67, v[220:221]
	v_lshl_add_u64 v[208:209], v[208:209], 0, v[250:251]
	v_pk_mul_f32 v[124:125], v[124:125], v[120:121]
	v_pk_mul_f32 v[126:127], v[126:127], v[122:123]
	v_pk_mul_f32 v[112:113], v[112:113], v[116:117]
	v_pk_mul_f32 v[114:115], v[114:115], v[118:119]
	v_cvt_pk_bf16_f32 v120, v124, v125
	v_cvt_pk_bf16_f32 v121, v126, v127
	v_cvt_pk_bf16_f32 v122, v112, v113
	v_cvt_pk_bf16_f32 v123, v114, v115
	global_store_dwordx4 v[208:209], v[120:123], off
	v_pk_mul_f32 v[108:109], v[108:109], v[232:233] op_sel_hi:[1,0]
	v_pk_mul_f32 v[110:111], v[110:111], v[232:233] op_sel_hi:[1,0]
	v_pk_mul_f32 v[100:101], v[100:101], v[232:233] op_sel_hi:[1,0]
	v_pk_mul_f32 v[102:103], v[102:103], v[232:233] op_sel_hi:[1,0]
	v_exp_f32_e32 v108, v108
	v_exp_f32_e32 v109, v109
	v_exp_f32_e32 v110, v110
	v_exp_f32_e32 v111, v111
	v_exp_f32_e32 v100, v100
	v_exp_f32_e32 v101, v101
	v_exp_f32_e32 v102, v102
	v_exp_f32_e32 v103, v103
	v_pk_mul_f32 v[104:105], v[104:105], v[232:233] op_sel:[0,1] op_sel_hi:[1,1]
	v_pk_mul_f32 v[106:107], v[106:107], v[232:233] op_sel:[0,1] op_sel_hi:[1,1]
	v_pk_mul_f32 v[96:97], v[96:97], v[232:233] op_sel:[0,1] op_sel_hi:[1,1]
	v_pk_mul_f32 v[98:99], v[98:99], v[232:233] op_sel:[0,1] op_sel_hi:[1,1]
	v_pk_add_f32 v[108:109], v[108:109], 1.0 op_sel_hi:[1,0]
	v_pk_add_f32 v[110:111], v[110:111], 1.0 op_sel_hi:[1,0]
	v_pk_add_f32 v[100:101], v[100:101], 1.0 op_sel_hi:[1,0]
	v_pk_add_f32 v[102:103], v[102:103], 1.0 op_sel_hi:[1,0]
	v_rcp_f32_e32 v108, v108
	v_rcp_f32_e32 v109, v109
	v_rcp_f32_e32 v110, v110
	v_rcp_f32_e32 v111, v111
	v_rcp_f32_e32 v100, v100
	v_rcp_f32_e32 v101, v101
	v_rcp_f32_e32 v102, v102
	v_rcp_f32_e32 v103, v103
	v_mad_i64_i32 v[208:209], s[4:5], v160, s67, v[220:221]
	v_lshl_add_u64 v[208:209], v[208:209], 0, v[250:251]
	v_pk_mul_f32 v[104:105], v[104:105], v[108:109]
	v_pk_mul_f32 v[106:107], v[106:107], v[110:111]
	v_pk_mul_f32 v[96:97], v[96:97], v[100:101]
	v_pk_mul_f32 v[98:99], v[98:99], v[102:103]
	v_cvt_pk_bf16_f32 v108, v104, v105
	v_cvt_pk_bf16_f32 v109, v106, v107
	v_cvt_pk_bf16_f32 v110, v96, v97
	v_cvt_pk_bf16_f32 v111, v98, v99
	global_store_dwordx4 v[208:209], v[108:111], off
	v_pk_mul_f32 v[92:93], v[92:93], v[234:235] op_sel_hi:[1,0]
	v_pk_mul_f32 v[94:95], v[94:95], v[234:235] op_sel_hi:[1,0]
	v_pk_mul_f32 v[84:85], v[84:85], v[234:235] op_sel_hi:[1,0]
	v_pk_mul_f32 v[86:87], v[86:87], v[234:235] op_sel_hi:[1,0]
; __device__ __forceinline__ unsigned cvt_pk_bf16(float lo, float hi) { unsigned r; asm volatile("v_cvt_pk_bf16_f32 %0, %1, %2" : "=v"(r) : "v"(lo), "v"(hi)); return r; }
; __device__ __forceinline__ float fast_rcp(float x) { return __builtin_amdgcn_rcpf(x); }
; __device__ __forceinline__ unsigned cvt_pk_bf16(float lo, float hi) { const f32x2 v = {lo, hi}; const bf16x2_t b = __builtin_convertvector(v, bf16x2_t); return __builtin_bit_cast(unsigned, b); }
;     __device__ __forceinline__ void operator()(const f32x4 (&acc)[2][2][4][2], const Unit& u, int wr, int wc, int fr, int fq) const {
;     ...
;                 const int r = row0 + ai * HALF + m * 16; const float rs = rsv[ai][m], nrs = rs * -1.4426950408889634f, rs2 = rs * rs;
;                 float o[8];
; #pragma unroll
;                 for (int n = 0; n < 2; ++n) {
;                     const f32x4 t = acc[ai][0][m][n] * nrs, p = (acc[ai][0][m][n] * acc[ai][1][m][n]) * rs2;
; #pragma unroll
;                     for (int j = 0; j < 4; ++j) o[4 * n + j] = p[j] * fast_rcp(1.0f + __builtin_amdgcn_exp2f(t[j]));
;                 }
;                 u32x4 w; w.x = cvt_pk_bf16(o[0], o[1]); w.y = cvt_pk_bf16(o[2], o[3]); w.z = cvt_pk_bf16(o[4], o[5]); w.w = cvt_pk_bf16(o[6], o[7]);
;                 *(u32x4*)(O + (size_t)r * ldo + col0) = w;
	v_exp_f32_e32 v92, v92
	v_exp_f32_e32 v93, v93
	v_exp_f32_e32 v94, v94
	v_exp_f32_e32 v95, v95
	v_exp_f32_e32 v84, v84
	v_exp_f32_e32 v85, v85
	v_exp_f32_e32 v86, v86
	v_exp_f32_e32 v87, v87
	v_pk_mul_f32 v[88:89], v[88:89], v[234:235] op_sel:[0,1] op_sel_hi:[1,1]
	v_pk_mul_f32 v[90:91], v[90:91], v[234:235] op_sel:[0,1] op_sel_hi:[1,1]
	v_pk_mul_f32 v[80:81], v[80:81], v[234:235] op_sel:[0,1] op_sel_hi:[1,1]
	v_pk_mul_f32 v[82:83], v[82:83], v[234:235] op_sel:[0,1] op_sel_hi:[1,1]
	v_pk_add_f32 v[92:93], v[92:93], 1.0 op_sel_hi:[1,0]
	v_pk_add_f32 v[94:95], v[94:95], 1.0 op_sel_hi:[1,0]
	v_pk_add_f32 v[84:85], v[84:85], 1.0 op_sel_hi:[1,0]
	v_pk_add_f32 v[86:87], v[86:87], 1.0 op_sel_hi:[1,0]
	v_rcp_f32_e32 v92, v92
	v_rcp_f32_e32 v93, v93
	v_rcp_f32_e32 v94, v94
	v_rcp_f32_e32 v95, v95
	v_rcp_f32_e32 v84, v84
	v_rcp_f32_e32 v85, v85
	v_rcp_f32_e32 v86, v86
	v_rcp_f32_e32 v87, v87
	v_mad_i64_i32 v[208:209], s[4:5], v158, s67, v[220:221]
	v_lshl_add_u64 v[208:209], v[208:209], 0, v[250:251]
	v_pk_mul_f32 v[88:89], v[88:89], v[92:93]
	v_pk_mul_f32 v[90:91], v[90:91], v[94:95]
	v_pk_mul_f32 v[80:81], v[80:81], v[84:85]
	v_pk_mul_f32 v[82:83], v[82:83], v[86:87]
	v_cvt_pk_bf16_f32 v92, v88, v89
	v_cvt_pk_bf16_f32 v93, v90, v91
	v_cvt_pk_bf16_f32 v94, v80, v81
	v_cvt_pk_bf16_f32 v95, v82, v83
	global_store_dwordx4 v[208:209], v[92:95], off
	v_pk_mul_f32 v[76:77], v[76:77], v[184:185] op_sel_hi:[1,0]
	v_pk_mul_f32 v[78:79], v[78:79], v[184:185] op_sel_hi:[1,0]
	v_pk_mul_f32 v[68:69], v[68:69], v[184:185] op_sel_hi:[1,0]
	v_pk_mul_f32 v[70:71], v[70:71], v[184:185] op_sel_hi:[1,0]
	v_exp_f32_e32 v76, v76
	v_exp_f32_e32 v77, v77
	v_exp_f32_e32 v78, v78
	v_exp_f32_e32 v79, v79
	v_exp_f32_e32 v68, v68
	v_exp_f32_e32 v69, v69
	v_exp_f32_e32 v70, v70
	v_exp_f32_e32 v71, v71
	v_pk_mul_f32 v[72:73], v[72:73], v[184:185] op_sel:[0,1] op_sel_hi:[1,1]
	v_pk_mul_f32 v[74:75], v[74:75], v[184:185] op_sel:[0,1] op_sel_hi:[1,1]
	v_pk_mul_f32 v[64:65], v[64:65], v[184:185] op_sel:[0,1] op_sel_hi:[1,1]
	v_pk_mul_f32 v[66:67], v[66:67], v[184:185] op_sel:[0,1] op_sel_hi:[1,1]
	v_pk_add_f32 v[76:77], v[76:77], 1.0 op_sel_hi:[1,0]
	v_pk_add_f32 v[78:79], v[78:79], 1.0 op_sel_hi:[1,0]
	v_pk_add_f32 v[68:69], v[68:69], 1.0 op_sel_hi:[1,0]
	v_pk_add_f32 v[70:71], v[70:71], 1.0 op_sel_hi:[1,0]
	v_rcp_f32_e32 v76, v76
	v_rcp_f32_e32 v77, v77
	v_rcp_f32_e32 v78, v78
	v_rcp_f32_e32 v79, v79
	v_rcp_f32_e32 v68, v68
	v_rcp_f32_e32 v69, v69
	v_rcp_f32_e32 v70, v70
	v_rcp_f32_e32 v71, v71
	v_mad_i64_i32 v[208:209], s[4:5], v156, s67, v[220:221]
	v_lshl_add_u64 v[208:209], v[208:209], 0, v[250:251]
	v_pk_mul_f32 v[72:73], v[72:73], v[76:77]
	v_pk_mul_f32 v[74:75], v[74:75], v[78:79]
	v_pk_mul_f32 v[64:65], v[64:65], v[68:69]
	v_pk_mul_f32 v[66:67], v[66:67], v[70:71]
	v_cvt_pk_bf16_f32 v76, v72, v73
	v_cvt_pk_bf16_f32 v77, v74, v75
	v_cvt_pk_bf16_f32 v78, v64, v65
	v_cvt_pk_bf16_f32 v79, v66, v67
	global_store_dwordx4 v[208:209], v[76:79], off
	v_pk_mul_f32 v[60:61], v[60:61], v[186:187] op_sel_hi:[1,0]
	v_pk_mul_f32 v[62:63], v[62:63], v[186:187] op_sel_hi:[1,0]
	v_pk_mul_f32 v[52:53], v[52:53], v[186:187] op_sel_hi:[1,0]
	v_pk_mul_f32 v[54:55], v[54:55], v[186:187] op_sel_hi:[1,0]
	v_exp_f32_e32 v60, v60
	v_exp_f32_e32 v61, v61
	v_exp_f32_e32 v62, v62
	v_exp_f32_e32 v63, v63
	v_exp_f32_e32 v52, v52
	v_exp_f32_e32 v53, v53
	v_exp_f32_e32 v54, v54
	v_exp_f32_e32 v55, v55
	v_pk_mul_f32 v[56:57], v[56:57], v[186:187] op_sel:[0,1] op_sel_hi:[1,1]
	v_pk_mul_f32 v[58:59], v[58:59], v[186:187] op_sel:[0,1] op_sel_hi:[1,1]
	v_pk_mul_f32 v[48:49], v[48:49], v[186:187] op_sel:[0,1] op_sel_hi:[1,1]
	v_pk_mul_f32 v[50:51], v[50:51], v[186:187] op_sel:[0,1] op_sel_hi:[1,1]
	v_pk_add_f32 v[60:61], v[60:61], 1.0 op_sel_hi:[1,0]
	v_pk_add_f32 v[62:63], v[62:63], 1.0 op_sel_hi:[1,0]
	v_pk_add_f32 v[52:53], v[52:53], 1.0 op_sel_hi:[1,0]
	v_pk_add_f32 v[54:55], v[54:55], 1.0 op_sel_hi:[1,0]
	v_rcp_f32_e32 v60, v60
	v_rcp_f32_e32 v61, v61
	v_rcp_f32_e32 v62, v62
	v_rcp_f32_e32 v63, v63
	v_rcp_f32_e32 v52, v52
	v_rcp_f32_e32 v53, v53
	v_rcp_f32_e32 v54, v54
	v_rcp_f32_e32 v55, v55
	v_mad_i64_i32 v[208:209], s[4:5], v154, s67, v[220:221]
	v_lshl_add_u64 v[208:209], v[208:209], 0, v[250:251]
	v_pk_mul_f32 v[56:57], v[56:57], v[60:61]
	v_pk_mul_f32 v[58:59], v[58:59], v[62:63]
	v_pk_mul_f32 v[48:49], v[48:49], v[52:53]
	v_pk_mul_f32 v[50:51], v[50:51], v[54:55]
	v_cvt_pk_bf16_f32 v60, v56, v57
	v_cvt_pk_bf16_f32 v61, v58, v59
	v_cvt_pk_bf16_f32 v62, v48, v49
	v_cvt_pk_bf16_f32 v63, v50, v51
	global_store_dwordx4 v[208:209], v[60:63], off
	v_pk_mul_f32 v[44:45], v[44:45], v[188:189] op_sel_hi:[1,0]
	v_pk_mul_f32 v[46:47], v[46:47], v[188:189] op_sel_hi:[1,0]
	v_pk_mul_f32 v[36:37], v[36:37], v[188:189] op_sel_hi:[1,0]
; __device__ __forceinline__ unsigned cvt_pk_bf16(float lo, float hi) { unsigned r; asm volatile("v_cvt_pk_bf16_f32 %0, %1, %2" : "=v"(r) : "v"(lo), "v"(hi)); return r; }
; __device__ __forceinline__ float fast_rcp(float x) { return __builtin_amdgcn_rcpf(x); }
; #define PG8_BAR __builtin_amdgcn_s_barrier()
; __device__ __forceinline__ unsigned cvt_pk_bf16(float lo, float hi) { const f32x2 v = {lo, hi}; const bf16x2_t b = __builtin_convertvector(v, bf16x2_t); return __builtin_bit_cast(unsigned, b); }
;     __device__ __forceinline__ void operator()(const f32x4 (&acc)[2][2][4][2], const Unit& u, int wr, int wc, int fr, int fq) const {
;     ...
;                 const int r = row0 + ai * HALF + m * 16; const float rs = rsv[ai][m], nrs = rs * -1.4426950408889634f, rs2 = rs * rs;
;                 float o[8];
; #pragma unroll
;                 for (int n = 0; n < 2; ++n) {
;                     const f32x4 t = acc[ai][0][m][n] * nrs, p = (acc[ai][0][m][n] * acc[ai][1][m][n]) * rs2;
; #pragma unroll
;                     for (int j = 0; j < 4; ++j) o[4 * n + j] = p[j] * fast_rcp(1.0f + __builtin_amdgcn_exp2f(t[j]));
;                 }
;                 u32x4 w; w.x = cvt_pk_bf16(o[0], o[1]); w.y = cvt_pk_bf16(o[2], o[3]); w.z = cvt_pk_bf16(o[4], o[5]); w.w = cvt_pk_bf16(o[6], o[7]);
;                 *(u32x4*)(O + (size_t)r * ldo + col0) = w;
; template <class Epi, class Sched, bool ALIGN_EPI = false, bool SP2 = false>
; __device__ __forceinline__ void gemm_phase(PG8_LAS unsigned char* lds, const Gemm g, const Sched& S, const Epi& E) {
;     ...
;         if (!has_next) break;
; #pragma unroll
;         for (int a = 0; a < 2; ++a)
; #pragma unroll
;             for (int b = 0; b < 2; ++b)
; #pragma unroll
;                 for (int m = 0; m < 4; ++m)
; #pragma unroll
;                     for (int n = 0; n < 2; ++n) acc[a][b][m][n] = (f32x4){0.f, 0.f, 0.f, 0.f};
;         cur = nxt; cA = nA; cB = nB; ++ui;
;         if constexpr (ALIGN_EPI) { if (wr == 1) PG8_BAR; }
	v_pk_mul_f32 v[38:39], v[38:39], v[188:189] op_sel_hi:[1,0]
	v_exp_f32_e32 v44, v44
	v_exp_f32_e32 v45, v45
	v_exp_f32_e32 v46, v46
	v_exp_f32_e32 v47, v47
	v_exp_f32_e32 v36, v36
	v_exp_f32_e32 v37, v37
	v_exp_f32_e32 v38, v38
	v_exp_f32_e32 v39, v39
	v_pk_mul_f32 v[40:41], v[40:41], v[188:189] op_sel:[0,1] op_sel_hi:[1,1]
	v_pk_mul_f32 v[42:43], v[42:43], v[188:189] op_sel:[0,1] op_sel_hi:[1,1]
	v_pk_mul_f32 v[32:33], v[32:33], v[188:189] op_sel:[0,1] op_sel_hi:[1,1]
	v_pk_mul_f32 v[34:35], v[34:35], v[188:189] op_sel:[0,1] op_sel_hi:[1,1]
	v_pk_add_f32 v[44:45], v[44:45], 1.0 op_sel_hi:[1,0]
	v_pk_add_f32 v[46:47], v[46:47], 1.0 op_sel_hi:[1,0]
	v_pk_add_f32 v[36:37], v[36:37], 1.0 op_sel_hi:[1,0]
	v_pk_add_f32 v[38:39], v[38:39], 1.0 op_sel_hi:[1,0]
	v_rcp_f32_e32 v44, v44
	v_rcp_f32_e32 v45, v45
	v_rcp_f32_e32 v46, v46
	v_rcp_f32_e32 v47, v47
	v_rcp_f32_e32 v36, v36
	v_rcp_f32_e32 v37, v37
	v_rcp_f32_e32 v38, v38
	v_rcp_f32_e32 v39, v39
	v_mad_i64_i32 v[208:209], s[4:5], v152, s67, v[220:221]
	v_lshl_add_u64 v[208:209], v[208:209], 0, v[250:251]
	v_pk_mul_f32 v[40:41], v[40:41], v[44:45]
	v_pk_mul_f32 v[42:43], v[42:43], v[46:47]
	v_pk_mul_f32 v[32:33], v[32:33], v[36:37]
	v_pk_mul_f32 v[34:35], v[34:35], v[38:39]
	v_cvt_pk_bf16_f32 v44, v40, v41
	v_cvt_pk_bf16_f32 v45, v42, v43
	v_cvt_pk_bf16_f32 v46, v32, v33
	v_cvt_pk_bf16_f32 v47, v34, v35
	global_store_dwordx4 v[208:209], v[44:47], off
	v_pk_mul_f32 v[28:29], v[28:29], v[190:191] op_sel_hi:[1,0]
	v_pk_mul_f32 v[30:31], v[30:31], v[190:191] op_sel_hi:[1,0]
	v_pk_mul_f32 v[20:21], v[20:21], v[190:191] op_sel_hi:[1,0]
	v_pk_mul_f32 v[22:23], v[22:23], v[190:191] op_sel_hi:[1,0]
	v_exp_f32_e32 v28, v28
	v_exp_f32_e32 v29, v29
	v_exp_f32_e32 v30, v30
	v_exp_f32_e32 v31, v31
	v_exp_f32_e32 v20, v20
	v_exp_f32_e32 v21, v21
	v_exp_f32_e32 v22, v22
	v_exp_f32_e32 v23, v23
	v_pk_mul_f32 v[24:25], v[24:25], v[190:191] op_sel:[0,1] op_sel_hi:[1,1]
	v_pk_mul_f32 v[26:27], v[26:27], v[190:191] op_sel:[0,1] op_sel_hi:[1,1]
	v_pk_mul_f32 v[16:17], v[16:17], v[190:191] op_sel:[0,1] op_sel_hi:[1,1]
	v_pk_mul_f32 v[18:19], v[18:19], v[190:191] op_sel:[0,1] op_sel_hi:[1,1]
	v_pk_add_f32 v[28:29], v[28:29], 1.0 op_sel_hi:[1,0]
	v_pk_add_f32 v[30:31], v[30:31], 1.0 op_sel_hi:[1,0]
	v_pk_add_f32 v[20:21], v[20:21], 1.0 op_sel_hi:[1,0]
	v_pk_add_f32 v[22:23], v[22:23], 1.0 op_sel_hi:[1,0]
	v_rcp_f32_e32 v28, v28
	v_rcp_f32_e32 v29, v29
	v_rcp_f32_e32 v30, v30
	v_rcp_f32_e32 v31, v31
	v_rcp_f32_e32 v20, v20
	v_rcp_f32_e32 v21, v21
	v_rcp_f32_e32 v22, v22
	v_rcp_f32_e32 v23, v23
	v_mad_i64_i32 v[208:209], s[4:5], v150, s67, v[220:221]
	v_lshl_add_u64 v[208:209], v[208:209], 0, v[250:251]
	v_pk_mul_f32 v[24:25], v[24:25], v[28:29]
	v_pk_mul_f32 v[26:27], v[26:27], v[30:31]
	v_pk_mul_f32 v[16:17], v[16:17], v[20:21]
	v_pk_mul_f32 v[18:19], v[18:19], v[22:23]
	v_cvt_pk_bf16_f32 v28, v24, v25
	v_cvt_pk_bf16_f32 v29, v26, v27
	v_cvt_pk_bf16_f32 v30, v16, v17
	v_cvt_pk_bf16_f32 v31, v18, v19
	global_store_dwordx4 v[208:209], v[28:31], off
	v_pk_mul_f32 v[12:13], v[12:13], v[204:205] op_sel_hi:[1,0]
	v_pk_mul_f32 v[14:15], v[14:15], v[204:205] op_sel_hi:[1,0]
	v_pk_mul_f32 v[4:5], v[4:5], v[204:205] op_sel_hi:[1,0]
	v_pk_mul_f32 v[6:7], v[6:7], v[204:205] op_sel_hi:[1,0]
	v_exp_f32_e32 v12, v12
	v_exp_f32_e32 v13, v13
	v_exp_f32_e32 v14, v14
	v_exp_f32_e32 v15, v15
	v_exp_f32_e32 v4, v4
	v_exp_f32_e32 v5, v5
	v_exp_f32_e32 v6, v6
	v_exp_f32_e32 v7, v7
	v_pk_mul_f32 v[8:9], v[8:9], v[204:205] op_sel:[0,1] op_sel_hi:[1,1]
	v_pk_mul_f32 v[10:11], v[10:11], v[204:205] op_sel:[0,1] op_sel_hi:[1,1]
	v_pk_mul_f32 v[0:1], v[0:1], v[204:205] op_sel:[0,1] op_sel_hi:[1,1]
	v_pk_mul_f32 v[2:3], v[2:3], v[204:205] op_sel:[0,1] op_sel_hi:[1,1]
	v_pk_add_f32 v[12:13], v[12:13], 1.0 op_sel_hi:[1,0]
	v_pk_add_f32 v[14:15], v[14:15], 1.0 op_sel_hi:[1,0]
	v_pk_add_f32 v[4:5], v[4:5], 1.0 op_sel_hi:[1,0]
	v_pk_add_f32 v[6:7], v[6:7], 1.0 op_sel_hi:[1,0]
	v_rcp_f32_e32 v12, v12
	v_rcp_f32_e32 v13, v13
	v_rcp_f32_e32 v14, v14
	v_rcp_f32_e32 v15, v15
	v_rcp_f32_e32 v4, v4
	v_rcp_f32_e32 v5, v5
	v_rcp_f32_e32 v6, v6
	v_rcp_f32_e32 v7, v7
	v_mad_i64_i32 v[208:209], s[4:5], v148, s67, v[220:221]
	v_lshl_add_u64 v[208:209], v[208:209], 0, v[250:251]
	v_pk_mul_f32 v[8:9], v[8:9], v[12:13]
	v_pk_mul_f32 v[10:11], v[10:11], v[14:15]
	v_pk_mul_f32 v[0:1], v[0:1], v[4:5]
	v_pk_mul_f32 v[2:3], v[2:3], v[6:7]
	v_cvt_pk_bf16_f32 v12, v8, v9
	v_cvt_pk_bf16_f32 v13, v10, v11
	v_cvt_pk_bf16_f32 v14, v0, v1
	v_cvt_pk_bf16_f32 v15, v2, v3
	global_store_dwordx4 v[208:209], v[12:15], off
	s_cbranch_vccnz .LBB0_1005
	s_andn2_b64 vcc, exec, s[14:15]
	s_cbranch_vccnz .LBB0_1004
	s_mov_b32 s87, 1
	s_branch .LBB0_1004
